# EpiResid epilogue row loops (down/out GEMMs): vmcnt(0) waits re-derived per first consumer (counted), residual-row prefetches stay in flight
# speedup vs baseline: 1.0174x; 1.0031x over previous
; #define RES_LOADG(slot, g_) do { const int ro_ = ((g_) >> 2) * HALF + ((g_) & 3) * 16; \
;                 _Pragma("unroll") for (int n = 0; n < 2; ++n) xa[slot][n] = *(const f32x4*)(sl + rbase + (size_t)ro_ * 2048 + bj * HALF + 4 * n); \
;                 ms[slot] = *(const f2_t_*)(stp + 2 * (row0 + ro_)); } while (0)
;     __device__ __forceinline__ void operator()(const f32x4 (&acc)[2][2][4][2], const Unit& u, int wr, int wc, int fr, int fq) const {
;     ...
;         for (int bj = 0; bj < 2; ++bj) {
;             f32x4 mv[2], ag[2], ab[2];
; #pragma unroll
;             for (int n = 0; n < 2; ++n) { mv[n] = *(const f32x4*)(mp + col0 + bj * HALF + 4 * n) * coef;
;                 const f32x4 g4 = *(const f32x4*)(lg + col0 + bj * HALF + 4 * n), b4 = *(const f32x4*)(lb + col0 + bj * HALF + 4 * n);
;                 const f32x4 g4s = ln ? g4 : (f32x4){1.f, 1.f, 1.f, 1.f}, b4s = ln ? b4 : (f32x4){0.f, 0.f, 0.f, 0.f};
;                 ag[n] = g4s * al; ab[n] = b4s * al; }
;             f32x4 xa[3][2]; f2_t_ ms[3];
;     ...
;             RES_LOADG(0, 0); RES_LOADG(1, 1);
; #pragma unroll
;             for (int gi = 0; gi < 8; ++gi) {
;                 const int ai = gi >> 2, m = gi & 3;
;                 if (gi + 2 < 8) RES_LOADG((gi + 2) % 3, gi + 2);
;                 asm volatile("" ::: "memory");
;                 float* rowp = xl + rbase + (size_t)(ai * HALF + m * 16) * 2048 + bj * HALF;
;                 const float mean = ln ? ms[gi % 3][0] : 0.f, rstd = ln ? ms[gi % 3][1] : 1.f;
; #pragma unroll
;                 for (int n = 0; n < 2; ++n) { const f32x4 t = ag[n] * rstd;
;                     *(f32x4*)(rowp + 4 * n) = (xa[gi % 3][n] - mean) * t + (ab[n] + mv[n] * acc[ai][bj][m][n]); }
.LBB0_327:
.LBB0_329:
	s_waitcnt vmcnt(0)
	v_pk_mul_f32 v[140:141], v[140:141], s[40:41] op_sel_hi:[1,0]
	v_pk_mul_f32 v[142:143], v[142:143], s[40:41] op_sel_hi:[1,0]
	v_cndmask_b32_e64 v190, v140, 0, s[28:29]
	v_lshl_add_u32 v140, s74, 8, v218
	v_cndmask_b32_e64 v191, v141, 0, s[28:29]
	v_ashrrev_i32_e32 v141, 31, v140
	v_cndmask_b32_e64 v205, v143, 0, s[28:29]
	v_cndmask_b32_e64 v204, v142, 0, s[28:29]
	v_lshlrev_b64 v[142:143], 11, v[140:141]
	v_lshl_add_u64 v[142:143], v[142:143], 0, v[148:149]
	v_lshlrev_b64 v[170:171], 2, v[142:143]
	v_pk_mul_f32 v[212:213], v[134:135], 0.5 op_sel_hi:[1,0]
	v_pk_mul_f32 v[210:211], v[132:133], 0.5 op_sel_hi:[1,0]
	v_pk_mul_f32 v[132:133], v[138:139], s[40:41] op_sel_hi:[1,0]
	v_pk_mul_f32 v[134:135], v[136:137], s[40:41] op_sel_hi:[1,0]
	v_lshl_add_u64 v[164:165], s[20:21], 0, v[170:171]
	s_mov_b64 s[40:41], 0x20000
	v_cndmask_b32_e64 v209, v133, 0, s[28:29]
	v_cndmask_b32_e64 v208, v132, 0, s[28:29]
	v_lshl_add_u64 v[132:133], v[164:165], 0, s[40:41]
	s_mov_b32 s40, 0x20000
	v_lshlrev_b32_e32 v140, 1, v140
	v_add_co_u32_e32 v176, vcc, s40, v164
	v_ashrrev_i32_e32 v141, 31, v140
	s_nop 0
	v_addc_co_u32_e32 v177, vcc, 0, v165, vcc
	v_pk_mul_f32 v[188:189], v[146:147], 0.5 op_sel_hi:[1,0]
	v_pk_mul_f32 v[186:187], v[144:145], 0.5 op_sel_hi:[1,0]
	v_lshl_add_u64 v[162:163], v[140:141], 2, s[34:35]
	global_load_dwordx4 v[148:151], v[164:165], off offset:16
	global_load_dwordx4 v[238:241], v[164:165], off
	global_load_dwordx4 v[144:147], v[176:177], off
	global_load_dwordx4 v[136:139], v[132:133], off offset:16
	global_load_dwordx2 v[222:223], v[162:163], off
	global_load_dwordx2 v[216:217], v[162:163], off offset:128
	s_mov_b64 s[42:43], 0x40000
	v_lshl_add_u64 v[132:133], v[164:165], 0, s[42:43]
	s_mov_b32 s42, 0x40000
	v_add_co_u32_e32 v178, vcc, s42, v164
	v_pk_fma_f32 v[130:131], v[130:131], v[212:213], v[204:205]
	s_nop 0
	v_addc_co_u32_e32 v179, vcc, 0, v165, vcc
	v_pk_fma_f32 v[128:129], v[128:129], v[210:211], v[190:191]
	v_cndmask_b32_e64 v207, v135, 0, s[28:29]
	v_cndmask_b32_e64 v206, v134, 0, s[28:29]
	global_load_dwordx4 v[140:143], v[178:179], off
	s_nop 0
	global_load_dwordx4 v[132:135], v[132:133], off offset:16
	s_nop 0
	global_load_dwordx2 v[214:215], v[162:163], off offset:256
	v_lshl_add_u64 v[170:171], s[8:9], 0, v[170:171]
	v_pk_fma_f32 v[126:127], v[126:127], v[188:189], v[208:209]
	v_pk_fma_f32 v[124:125], v[124:125], v[186:187], v[206:207]
	s_mov_b32 s43, 0x60000
	s_mov_b64 s[74:75], 0x60000
	v_pk_fma_f32 v[120:121], v[120:121], v[210:211], v[190:191]
	v_pk_fma_f32 v[122:123], v[122:123], v[212:213], v[204:205]
	v_pk_fma_f32 v[118:119], v[118:119], v[188:189], v[208:209]
	v_pk_fma_f32 v[116:117], v[116:117], v[186:187], v[206:207]
	v_pk_fma_f32 v[112:113], v[112:113], v[210:211], v[190:191]
	v_pk_fma_f32 v[114:115], v[114:115], v[212:213], v[204:205]
	v_pk_fma_f32 v[108:109], v[108:109], v[186:187], v[206:207]
	v_pk_fma_f32 v[110:111], v[110:111], v[188:189], v[208:209]
	v_pk_fma_f32 v[104:105], v[104:105], v[210:211], v[190:191]
	v_pk_fma_f32 v[106:107], v[106:107], v[212:213], v[204:205]
	v_pk_fma_f32 v[102:103], v[102:103], v[188:189], v[208:209]
	v_pk_fma_f32 v[100:101], v[100:101], v[186:187], v[206:207]
	v_pk_fma_f32 v[98:99], v[98:99], v[212:213], v[204:205]
	v_pk_fma_f32 v[96:97], v[96:97], v[210:211], v[190:191]
	v_pk_fma_f32 v[94:95], v[94:95], v[188:189], v[208:209]
	v_pk_fma_f32 v[92:93], v[92:93], v[186:187], v[206:207]
	v_pk_fma_f32 v[90:91], v[90:91], v[212:213], v[204:205]
	v_pk_fma_f32 v[88:89], v[88:89], v[210:211], v[190:191]
	v_pk_fma_f32 v[86:87], v[86:87], v[188:189], v[208:209]
	v_pk_fma_f32 v[84:85], v[84:85], v[186:187], v[206:207]
	v_pk_fma_f32 v[80:81], v[80:81], v[210:211], v[190:191]
	v_pk_fma_f32 v[82:83], v[82:83], v[212:213], v[204:205]
	v_pk_fma_f32 v[78:79], v[78:79], v[188:189], v[208:209]
	v_pk_fma_f32 v[76:77], v[76:77], v[186:187], v[206:207]
	v_pk_fma_f32 v[74:75], v[74:75], v[212:213], v[204:205]
	v_pk_fma_f32 v[72:73], v[72:73], v[210:211], v[190:191]
	v_pk_fma_f32 v[70:71], v[70:71], v[188:189], v[208:209]
	v_pk_fma_f32 v[68:69], v[68:69], v[186:187], v[206:207]
	s_waitcnt vmcnt(4)
	v_cndmask_b32_e64 v192, v222, 0, s[28:29]
	v_cndmask_b32_e64 v222, v223, 1.0, s[28:29]
	v_pk_mul_f32 v[230:231], v[182:183], v[222:223] op_sel_hi:[1,0]
	v_pk_mul_f32 v[232:233], v[180:181], v[222:223] op_sel_hi:[1,0]
	v_sub_f32_e32 v239, v239, v192
	v_sub_f32_e32 v238, v238, v192
	v_sub_f32_e32 v241, v241, v192
	v_sub_f32_e32 v240, v240, v192
	v_pk_fma_f32 v[130:131], v[232:233], v[240:241], v[130:131]
	v_pk_fma_f32 v[128:129], v[230:231], v[238:239], v[128:129]
	global_store_dwordx4 v[170:171], v[128:131], off
	v_sub_f32_e32 v149, v149, v192
	v_sub_f32_e32 v148, v148, v192
	v_pk_mul_f32 v[128:129], v[174:175], v[222:223] op_sel_hi:[1,0]
	v_pk_mul_f32 v[130:131], v[184:185], v[222:223] op_sel_hi:[1,0]
	v_sub_f32_e32 v151, v151, v192
	v_sub_f32_e32 v150, v150, v192
	v_pk_fma_f32 v[126:127], v[130:131], v[150:151], v[126:127]
	v_pk_fma_f32 v[124:125], v[128:129], v[148:149], v[124:125]
	global_store_dwordx4 v[170:171], v[124:127], off offset:16
	v_add_co_u32_e32 v148, vcc, s43, v164
	s_nop 0
	v_lshl_add_u64 v[124:125], v[164:165], 0, s[74:75]
	v_addc_co_u32_e32 v149, vcc, 0, v165, vcc
	global_load_dwordx4 v[128:131], v[148:149], off
	s_nop 0
	global_load_dwordx4 v[124:127], v[124:125], off offset:16
	s_nop 0
	global_load_dwordx2 v[150:151], v[162:163], off offset:384
	s_waitcnt vmcnt(8)
; #define RES_LOADG(slot, g_) do { const int ro_ = ((g_) >> 2) * HALF + ((g_) & 3) * 16; \
;                 _Pragma("unroll") for (int n = 0; n < 2; ++n) xa[slot][n] = *(const f32x4*)(sl + rbase + (size_t)ro_ * 2048 + bj * HALF + 4 * n); \
;                 ms[slot] = *(const f2_t_*)(stp + 2 * (row0 + ro_)); } while (0)
;     __device__ __forceinline__ void operator()(const f32x4 (&acc)[2][2][4][2], const Unit& u, int wr, int wc, int fr, int fq) const {
;     ...
;             for (int gi = 0; gi < 8; ++gi) {
;                 const int ai = gi >> 2, m = gi & 3;
;                 if (gi + 2 < 8) RES_LOADG((gi + 2) % 3, gi + 2);
;                 asm volatile("" ::: "memory");
;                 float* rowp = xl + rbase + (size_t)(ai * HALF + m * 16) * 2048 + bj * HALF;
;                 const float mean = ln ? ms[gi % 3][0] : 0.f, rstd = ln ? ms[gi % 3][1] : 1.f;
; #pragma unroll
;                 for (int n = 0; n < 2; ++n) { const f32x4 t = ag[n] * rstd;
;                     *(f32x4*)(rowp + 4 * n) = (xa[gi % 3][n] - mean) * t + (ab[n] + mv[n] * acc[ai][bj][m][n]); }
;                 asm volatile("" ::: "memory");
	v_cndmask_b32_e64 v192, v216, 0, s[28:29]
	v_cndmask_b32_e64 v216, v217, 1.0, s[28:29]
	v_pk_mul_f32 v[222:223], v[182:183], v[216:217] op_sel_hi:[1,0]
	v_sub_f32_e32 v145, v145, v192
	v_sub_f32_e32 v144, v144, v192
	v_pk_mul_f32 v[230:231], v[180:181], v[216:217] op_sel_hi:[1,0]
	v_sub_f32_e32 v147, v147, v192
	v_sub_f32_e32 v146, v146, v192
	v_pk_fma_f32 v[120:121], v[222:223], v[144:145], v[120:121]
	v_add_co_u32_e32 v144, vcc, s40, v170
	v_pk_fma_f32 v[122:123], v[230:231], v[146:147], v[122:123]
	s_nop 0
	v_addc_co_u32_e32 v145, vcc, 0, v171, vcc
	global_store_dwordx4 v[144:145], v[120:123], off
	v_sub_f32_e32 v137, v137, v192
	v_sub_f32_e32 v136, v136, v192
	v_pk_mul_f32 v[120:121], v[174:175], v[216:217] op_sel_hi:[1,0]
	v_pk_mul_f32 v[122:123], v[184:185], v[216:217] op_sel_hi:[1,0]
	v_sub_f32_e32 v139, v139, v192
	v_sub_f32_e32 v138, v138, v192
	v_pk_fma_f32 v[118:119], v[122:123], v[138:139], v[118:119]
	v_pk_fma_f32 v[116:117], v[120:121], v[136:137], v[116:117]
	s_mov_b64 s[40:41], 0x100000
	global_store_dwordx4 v[144:145], v[116:119], off offset:16
	s_waitcnt vmcnt(7)
	v_cndmask_b32_e64 v192, v214, 0, s[28:29]
	v_cndmask_b32_e64 v214, v215, 1.0, s[28:29]
	v_lshl_add_u64 v[116:117], v[164:165], 0, s[40:41]
	s_mov_b32 s40, 0x100000
	v_add_co_u32_e32 v138, vcc, s40, v164
	v_pk_mul_f32 v[136:137], v[182:183], v[214:215] op_sel_hi:[1,0]
	s_nop 0
	v_addc_co_u32_e32 v139, vcc, 0, v165, vcc
	global_load_dwordx4 v[120:123], v[138:139], off
	s_nop 0
	global_load_dwordx4 v[116:119], v[116:117], off offset:16
	s_nop 0
	global_load_dwordx2 v[146:147], v[162:163], off offset:1024
	v_sub_f32_e32 v141, v141, v192
	v_sub_f32_e32 v140, v140, v192
	v_pk_mul_f32 v[216:217], v[180:181], v[214:215] op_sel_hi:[1,0]
	v_sub_f32_e32 v143, v143, v192
	v_sub_f32_e32 v142, v142, v192
	v_pk_fma_f32 v[112:113], v[136:137], v[140:141], v[112:113]
	v_add_co_u32_e32 v136, vcc, s42, v170
	v_pk_fma_f32 v[114:115], v[216:217], v[142:143], v[114:115]
	s_nop 0
	v_addc_co_u32_e32 v137, vcc, 0, v171, vcc
	global_store_dwordx4 v[136:137], v[112:115], off
	v_sub_f32_e32 v133, v133, v192
	v_sub_f32_e32 v132, v132, v192
	v_pk_mul_f32 v[112:113], v[174:175], v[214:215] op_sel_hi:[1,0]
	s_mov_b32 s41, 0x120000
	v_pk_mul_f32 v[114:115], v[184:185], v[214:215] op_sel_hi:[1,0]
	v_sub_f32_e32 v135, v135, v192
	v_sub_f32_e32 v134, v134, v192
	v_pk_fma_f32 v[108:109], v[112:113], v[132:133], v[108:109]
	v_add_co_u32_e32 v132, vcc, s41, v164
	v_pk_fma_f32 v[110:111], v[114:115], v[134:135], v[110:111]
	s_nop 0
	v_addc_co_u32_e32 v133, vcc, 0, v165, vcc
	global_store_dwordx4 v[136:137], v[108:111], off offset:16
	s_mov_b64 s[74:75], 0x120000
	s_waitcnt vmcnt(7)
	v_cndmask_b32_e64 v141, v150, 0, s[28:29]
	v_cndmask_b32_e64 v140, v151, 1.0, s[28:29]
	v_pk_mul_f32 v[142:143], v[182:183], v[140:141] op_sel_hi:[1,0]
	v_sub_f32_e32 v129, v129, v141
	v_sub_f32_e32 v128, v128, v141
	v_pk_mul_f32 v[150:151], v[180:181], v[140:141] op_sel_hi:[1,0]
	v_sub_f32_e32 v131, v131, v141
	v_sub_f32_e32 v130, v130, v141
	v_pk_fma_f32 v[128:129], v[142:143], v[128:129], v[104:105]
	v_add_co_u32_e32 v104, vcc, s43, v170
	v_lshl_add_u64 v[108:109], v[164:165], 0, s[74:75]
	v_pk_fma_f32 v[130:131], v[150:151], v[130:131], v[106:107]
	v_addc_co_u32_e32 v105, vcc, 0, v171, vcc
	global_load_dwordx4 v[112:115], v[132:133], off
	s_nop 0
	global_load_dwordx4 v[108:111], v[108:109], off offset:16
	s_nop 0
	global_load_dwordx2 v[134:135], v[162:163], off offset:1152
	global_store_dwordx4 v[104:105], v[128:131], off
	v_pk_mul_f32 v[106:107], v[174:175], v[140:141] op_sel_hi:[1,0]
	v_sub_f32_e32 v125, v125, v141
	v_pk_mul_f32 v[128:129], v[184:185], v[140:141] op_sel_hi:[1,0]
	v_sub_f32_e32 v124, v124, v141
	v_sub_f32_e32 v127, v127, v141
	v_sub_f32_e32 v126, v126, v141
	v_pk_fma_f32 v[102:103], v[128:129], v[126:127], v[102:103]
	v_pk_fma_f32 v[100:101], v[106:107], v[124:125], v[100:101]
	s_mov_b64 s[42:43], 0x140000
	global_store_dwordx4 v[104:105], v[100:103], off offset:16
	s_mov_b64 s[74:75], 0x160000
	s_waitcnt vmcnt(7)
	v_cndmask_b32_e64 v146, v146, 0, s[28:29]
	v_lshl_add_u64 v[102:103], v[164:165], 0, s[42:43]
	s_mov_b32 s42, 0x140000
	v_add_co_u32_e32 v100, vcc, s42, v164
	v_cndmask_b32_e64 v106, v147, 1.0, s[28:29]
	s_nop 0
	v_addc_co_u32_e32 v101, vcc, 0, v165, vcc
	global_load_dwordx4 v[124:127], v[100:101], off
	global_load_dwordx4 v[128:131], v[102:103], off offset:16
	s_nop 0
	global_load_dwordx2 v[102:103], v[162:163], off offset:1280
	v_pk_mul_f32 v[140:141], v[182:183], v[106:107] op_sel_hi:[1,0]
	v_pk_mul_f32 v[142:143], v[180:181], v[106:107] op_sel_hi:[1,0]
	v_sub_f32_e32 v121, v121, v146
	v_sub_f32_e32 v120, v120, v146
	v_sub_f32_e32 v123, v123, v146
	v_sub_f32_e32 v122, v122, v146
	v_pk_fma_f32 v[122:123], v[142:143], v[122:123], v[98:99]
	v_pk_fma_f32 v[120:121], v[140:141], v[120:121], v[96:97]
	v_add_co_u32_e32 v96, vcc, s40, v170
	v_pk_mul_f32 v[98:99], v[174:175], v[106:107] op_sel_hi:[1,0]
	v_pk_mul_f32 v[106:107], v[184:185], v[106:107] op_sel_hi:[1,0]
	v_sub_f32_e32 v117, v117, v146
	v_sub_f32_e32 v116, v116, v146
	v_sub_f32_e32 v119, v119, v146
	v_sub_f32_e32 v118, v118, v146
	v_addc_co_u32_e32 v97, vcc, 0, v171, vcc
	v_pk_fma_f32 v[94:95], v[106:107], v[118:119], v[94:95]
	v_pk_fma_f32 v[92:93], v[98:99], v[116:117], v[92:93]
	s_mov_b32 s40, 0x160000
	global_store_dwordx4 v[96:97], v[120:123], off
	global_store_dwordx4 v[96:97], v[92:95], off offset:16
	s_waitcnt vmcnt(7)
; #define RES_LOADG(slot, g_) do { const int ro_ = ((g_) >> 2) * HALF + ((g_) & 3) * 16; \
;                 _Pragma("unroll") for (int n = 0; n < 2; ++n) xa[slot][n] = *(const f32x4*)(sl + rbase + (size_t)ro_ * 2048 + bj * HALF + 4 * n); \
;                 ms[slot] = *(const f2_t_*)(stp + 2 * (row0 + ro_)); } while (0)
;     __device__ __forceinline__ void operator()(const f32x4 (&acc)[2][2][4][2], const Unit& u, int wr, int wc, int fr, int fq) const {
;     ...
;             for (int n = 0; n < 2; ++n) { mv[n] = *(const f32x4*)(mp + col0 + bj * HALF + 4 * n) * coef;
;                 const f32x4 g4 = *(const f32x4*)(lg + col0 + bj * HALF + 4 * n), b4 = *(const f32x4*)(lb + col0 + bj * HALF + 4 * n);
;                 const f32x4 g4s = ln ? g4 : (f32x4){1.f, 1.f, 1.f, 1.f}, b4s = ln ? b4 : (f32x4){0.f, 0.f, 0.f, 0.f};
;                 ag[n] = g4s * al; ab[n] = b4s * al; }
;     ...
;             for (int gi = 0; gi < 8; ++gi) {
;                 const int ai = gi >> 2, m = gi & 3;
;                 if (gi + 2 < 8) RES_LOADG((gi + 2) % 3, gi + 2);
;                 asm volatile("" ::: "memory");
;                 float* rowp = xl + rbase + (size_t)(ai * HALF + m * 16) * 2048 + bj * HALF;
;                 const float mean = ln ? ms[gi % 3][0] : 0.f, rstd = ln ? ms[gi % 3][1] : 1.f;
; #pragma unroll
;                 for (int n = 0; n < 2; ++n) { const f32x4 t = ag[n] * rstd;
;                     *(f32x4*)(rowp + 4 * n) = (xa[gi % 3][n] - mean) * t + (ab[n] + mv[n] * acc[ai][bj][m][n]); }
;                 asm volatile("" ::: "memory");
	v_cndmask_b32_e64 v140, v134, 0, s[28:29]
	v_add_co_u32_e32 v92, vcc, s40, v164
	v_lshl_add_u64 v[94:95], v[164:165], 0, s[74:75]
	s_nop 0
	v_addc_co_u32_e32 v93, vcc, 0, v165, vcc
	global_load_dwordx4 v[116:119], v[92:93], off
	global_load_dwordx4 v[120:123], v[94:95], off offset:16
	s_nop 0
	global_load_dwordx2 v[94:95], v[162:163], off offset:1408
	v_cndmask_b32_e64 v98, v135, 1.0, s[28:29]
	v_pk_mul_f32 v[106:107], v[182:183], v[98:99] op_sel_hi:[1,0]
	v_pk_mul_f32 v[134:135], v[180:181], v[98:99] op_sel_hi:[1,0]
	v_sub_f32_e32 v113, v113, v140
	v_sub_f32_e32 v112, v112, v140
	v_sub_f32_e32 v115, v115, v140
	v_sub_f32_e32 v114, v114, v140
	v_pk_fma_f32 v[114:115], v[134:135], v[114:115], v[90:91]
	v_pk_fma_f32 v[112:113], v[106:107], v[112:113], v[88:89]
	v_add_co_u32_e32 v88, vcc, s41, v170
	v_pk_mul_f32 v[90:91], v[174:175], v[98:99] op_sel_hi:[1,0]
	v_pk_mul_f32 v[98:99], v[184:185], v[98:99] op_sel_hi:[1,0]
	v_sub_f32_e32 v107, v109, v140
	v_sub_f32_e32 v106, v108, v140
	v_sub_f32_e32 v109, v111, v140
	v_sub_f32_e32 v108, v110, v140
	v_addc_co_u32_e32 v89, vcc, 0, v171, vcc
	v_pk_fma_f32 v[86:87], v[98:99], v[108:109], v[86:87]
	v_pk_fma_f32 v[84:85], v[90:91], v[106:107], v[84:85]
	global_store_dwordx4 v[88:89], v[84:87], off offset:16
	s_waitcnt vmcnt(6)
	v_cndmask_b32_e64 v106, v102, 0, s[28:29]
	v_sub_f32_e32 v99, v125, v106
	v_cndmask_b32_e64 v86, v103, 1.0, s[28:29]
	v_pk_mul_f32 v[84:85], v[182:183], v[86:87] op_sel_hi:[1,0]
	v_sub_f32_e32 v98, v124, v106
	global_store_dwordx4 v[88:89], v[112:115], off
	v_pk_mul_f32 v[90:91], v[180:181], v[86:87] op_sel_hi:[1,0]
	v_sub_f32_e32 v103, v127, v106
	v_sub_f32_e32 v102, v126, v106
	v_pk_fma_f32 v[80:81], v[84:85], v[98:99], v[80:81]
	v_add_co_u32_e32 v84, vcc, s42, v170
	v_pk_fma_f32 v[82:83], v[90:91], v[102:103], v[82:83]
	s_nop 0
	v_addc_co_u32_e32 v85, vcc, 0, v171, vcc
	global_store_dwordx4 v[84:85], v[80:83], off
	v_sub_f32_e32 v91, v131, v106
	v_sub_f32_e32 v90, v130, v106
	v_pk_mul_f32 v[80:81], v[174:175], v[86:87] op_sel_hi:[1,0]
	v_pk_mul_f32 v[82:83], v[184:185], v[86:87] op_sel_hi:[1,0]
	v_sub_f32_e32 v87, v129, v106
	v_sub_f32_e32 v86, v128, v106
	v_pk_fma_f32 v[78:79], v[82:83], v[90:91], v[78:79]
	v_pk_fma_f32 v[76:77], v[80:81], v[86:87], v[76:77]
	global_store_dwordx4 v[84:85], v[76:79], off offset:16
	v_mov_b32_e32 v91, 0x3fb504f3
	s_waitcnt vmcnt(4)
	v_cndmask_b32_e64 v90, v94, 0, s[28:29]
	v_cndmask_b32_e64 v76, v95, 1.0, s[28:29]
	v_pk_mul_f32 v[80:81], v[180:181], v[76:77] op_sel_hi:[1,0]
	v_sub_f32_e32 v87, v119, v90
	v_sub_f32_e32 v86, v118, v90
	v_pk_mul_f32 v[78:79], v[182:183], v[76:77] op_sel_hi:[1,0]
	v_sub_f32_e32 v83, v117, v90
	v_sub_f32_e32 v82, v116, v90
	v_pk_fma_f32 v[74:75], v[80:81], v[86:87], v[74:75]
	v_add_co_u32_e32 v86, vcc, s40, v170
	v_pk_fma_f32 v[72:73], v[78:79], v[82:83], v[72:73]
	s_nop 0
	v_addc_co_u32_e32 v87, vcc, 0, v171, vcc
	global_store_dwordx4 v[86:87], v[72:75], off
	v_sub_f32_e32 v79, v123, v90
	v_sub_f32_e32 v78, v122, v90
	v_pk_mul_f32 v[72:73], v[174:175], v[76:77] op_sel_hi:[1,0]
	v_pk_mul_f32 v[74:75], v[184:185], v[76:77] op_sel_hi:[1,0]
	v_sub_f32_e32 v77, v121, v90
	v_sub_f32_e32 v76, v120, v90
	v_pk_fma_f32 v[70:71], v[74:75], v[78:79], v[70:71]
	v_pk_fma_f32 v[68:69], v[72:73], v[76:77], v[68:69]
	global_store_dwordx4 v[86:87], v[68:71], off offset:16
	global_load_dwordx4 v[68:71], v[172:173], off offset:512
	global_load_dwordx4 v[80:83], v[166:167], off offset:512
	s_mov_b32 s40, 0x3fb504f3
	v_mov_b32_e32 v90, 0x3fb504f3
	s_and_b64 vcc, exec, s[4:5]
	v_mov_b32_e32 v94, 0x3fb504f3
	v_mov_b32_e32 v95, 0x3fb504f3
	global_load_dwordx4 v[76:79], v[172:173], off offset:528
	global_load_dwordx4 v[72:75], v[166:167], off offset:528
	s_cbranch_vccnz .LBB0_333
	global_load_dwordx4 v[244:247], v[168:169], off offset:512
	global_load_dwordx4 v[106:109], v[168:169], off offset:528
	s_waitcnt vmcnt(0)
	v_pk_mul_f32 v[94:95], v[246:247], s[40:41] op_sel_hi:[1,0]
	v_pk_mul_f32 v[90:91], v[244:245], s[40:41] op_sel_hi:[1,0]
	v_pk_mul_f32 v[102:103], v[82:83], s[40:41] op_sel_hi:[1,0]
	v_pk_mul_f32 v[98:99], v[80:81], s[40:41] op_sel_hi:[1,0]
	v_pk_mul_f32 v[82:83], v[108:109], s[40:41] op_sel_hi:[1,0]
	v_pk_mul_f32 v[80:81], v[106:107], s[40:41] op_sel_hi:[1,0]
	s_branch .LBB0_334

; #define RES_LOADG(slot, g_) do { const int ro_ = ((g_) >> 2) * HALF + ((g_) & 3) * 16; \
;                 _Pragma("unroll") for (int n = 0; n < 2; ++n) xa[slot][n] = *(const f32x4*)(sl + rbase + (size_t)ro_ * 2048 + bj * HALF + 4 * n); \
;                 ms[slot] = *(const f2_t_*)(stp + 2 * (row0 + ro_)); } while (0)
;     __device__ __forceinline__ void operator()(const f32x4 (&acc)[2][2][4][2], const Unit& u, int wr, int wc, int fr, int fq) const {
;     ...
;             f32x4 xa[3][2]; f2_t_ ms[3];
;     ...
;             RES_LOADG(0, 0); RES_LOADG(1, 1);
; #pragma unroll
;             for (int gi = 0; gi < 8; ++gi) {
;                 const int ai = gi >> 2, m = gi & 3;
;                 if (gi + 2 < 8) RES_LOADG((gi + 2) % 3, gi + 2);
;                 asm volatile("" ::: "memory");
;                 float* rowp = xl + rbase + (size_t)(ai * HALF + m * 16) * 2048 + bj * HALF;
;                 const float mean = ln ? ms[gi % 3][0] : 0.f, rstd = ln ? ms[gi % 3][1] : 1.f;
; #pragma unroll
;                 for (int n = 0; n < 2; ++n) { const f32x4 t = ag[n] * rstd;
;                     *(f32x4*)(rowp + 4 * n) = (xa[gi % 3][n] - mean) * t + (ab[n] + mv[n] * acc[ai][bj][m][n]); }
.LBB0_334:
	global_load_dwordx2 v[134:135], v[162:163], off
	global_load_dwordx2 v[140:141], v[162:163], off offset:128
	global_load_dwordx4 v[116:119], v[164:165], off offset:512
	global_load_dwordx4 v[120:123], v[164:165], off offset:528
	global_load_dwordx4 v[124:127], v[176:177], off offset:512
	s_mov_b64 s[4:5], 0x20200
	v_lshl_add_u64 v[106:107], v[164:165], 0, s[4:5]
	global_load_dwordx4 v[128:131], v[106:107], off offset:16
	v_pk_mul_f32 v[108:109], v[70:71], 0.5 op_sel_hi:[1,0]
	v_pk_mul_f32 v[70:71], v[72:73], s[40:41] op_sel_hi:[1,0]
	v_pk_mul_f32 v[76:77], v[76:77], 0.5 op_sel_hi:[1,0]
	v_pk_mul_f32 v[106:107], v[68:69], 0.5 op_sel_hi:[1,0]
	v_pk_mul_f32 v[68:69], v[74:75], s[40:41] op_sel_hi:[1,0]
	v_cndmask_b32_e64 v111, v71, 0, s[28:29]
	v_cndmask_b32_e64 v110, v70, 0, s[28:29]
	v_pk_mul_f32 v[78:79], v[78:79], 0.5 op_sel_hi:[1,0]
	s_mov_b64 s[4:5], 0x40200
	v_cndmask_b32_e64 v113, v69, 0, s[28:29]
	v_cndmask_b32_e64 v112, v68, 0, s[28:29]
	v_pk_fma_f32 v[166:167], v[52:53], v[76:77], v[110:111]
	v_lshl_add_u64 v[142:143], v[164:165], 0, s[4:5]
	v_pk_fma_f32 v[66:67], v[66:67], v[108:109], v[102:103]
	v_pk_fma_f32 v[64:65], v[64:65], v[106:107], v[98:99]
	v_pk_fma_f32 v[150:151], v[54:55], v[78:79], v[112:113]
	global_load_dwordx2 v[114:115], v[162:163], off offset:256
	global_load_dwordx4 v[72:75], v[178:179], off offset:512
	global_load_dwordx4 v[68:71], v[142:143], off offset:16
	v_pk_fma_f32 v[142:143], v[60:61], v[106:107], v[98:99]
	v_pk_fma_f32 v[58:59], v[58:59], v[78:79], v[112:113]
	v_pk_fma_f32 v[56:57], v[56:57], v[76:77], v[110:111]
	s_mov_b64 s[4:5], 0x60200
	v_pk_fma_f32 v[62:63], v[62:63], v[108:109], v[102:103]
	v_lshl_add_u64 v[146:147], v[164:165], 0, s[4:5]
	s_mov_b64 s[4:5], 0x100200
	v_pk_fma_f32 v[50:51], v[50:51], v[108:109], v[102:103]
	v_pk_fma_f32 v[48:49], v[48:49], v[106:107], v[98:99]
	v_pk_fma_f32 v[40:41], v[40:41], v[76:77], v[110:111]
	v_pk_fma_f32 v[46:47], v[46:47], v[108:109], v[102:103]
	v_pk_fma_f32 v[44:45], v[44:45], v[106:107], v[98:99]
	v_pk_fma_f32 v[26:27], v[26:27], v[108:109], v[102:103]
	v_pk_fma_f32 v[24:25], v[24:25], v[106:107], v[98:99]
	v_pk_fma_f32 v[14:15], v[14:15], v[78:79], v[112:113]
	v_pk_fma_f32 v[12:13], v[12:13], v[76:77], v[110:111]
	v_pk_fma_f32 v[22:23], v[22:23], v[108:109], v[102:103]
	v_pk_fma_f32 v[20:21], v[20:21], v[106:107], v[98:99]
	v_pk_fma_f32 v[18:19], v[18:19], v[108:109], v[102:103]
	v_pk_fma_f32 v[16:17], v[16:17], v[106:107], v[98:99]
	s_and_b64 vcc, exec, s[2:3]
	s_mov_b64 s[2:3], -1
	s_waitcnt vmcnt(8)
	v_cndmask_b32_e64 v53, v134, 0, s[28:29]
	v_cndmask_b32_e64 v52, v135, 1.0, s[28:29]
	v_pk_mul_f32 v[134:135], v[90:91], v[52:53] op_sel_hi:[1,0]
	v_pk_mul_f32 v[54:55], v[94:95], v[52:53] op_sel_hi:[1,0]
	s_waitcnt vmcnt(6)
	v_sub_f32_e32 v117, v117, v53
	v_sub_f32_e32 v116, v116, v53
	v_sub_f32_e32 v119, v119, v53
	v_sub_f32_e32 v118, v118, v53
	v_cndmask_b32_e64 v61, v140, 0, s[28:29]
	v_cndmask_b32_e64 v60, v141, 1.0, s[28:29]
	v_pk_mul_f32 v[140:141], v[80:81], v[52:53] op_sel_hi:[1,0]
	v_pk_mul_f32 v[168:169], v[82:83], v[52:53] op_sel_hi:[1,0]
	s_waitcnt vmcnt(5)
	v_sub_f32_e32 v121, v121, v53
	v_sub_f32_e32 v120, v120, v53
	v_sub_f32_e32 v123, v123, v53
	v_sub_f32_e32 v122, v122, v53
	v_pk_fma_f32 v[54:55], v[54:55], v[118:119], v[66:67]
	v_pk_fma_f32 v[52:53], v[134:135], v[116:117], v[64:65]
	v_pk_fma_f32 v[58:59], v[168:169], v[122:123], v[58:59]
	v_pk_fma_f32 v[56:57], v[140:141], v[120:121], v[56:57]
	global_store_dwordx4 v[170:171], v[52:55], off offset:512
	global_store_dwordx4 v[170:171], v[56:59], off offset:528
	v_pk_mul_f32 v[172:173], v[90:91], v[60:61] op_sel_hi:[1,0]
	v_pk_mul_f32 v[174:175], v[94:95], v[60:61] op_sel_hi:[1,0]
	s_waitcnt vmcnt(6)
	v_sub_f32_e32 v125, v125, v61
	v_sub_f32_e32 v124, v124, v61
	v_sub_f32_e32 v127, v127, v61
	global_load_dwordx2 v[116:117], v[162:163], off offset:384
	v_sub_f32_e32 v126, v126, v61
	v_pk_mul_f32 v[64:65], v[80:81], v[60:61] op_sel_hi:[1,0]
	v_pk_mul_f32 v[66:67], v[82:83], v[60:61] op_sel_hi:[1,0]
	global_load_dwordx4 v[52:55], v[148:149], off offset:512
	s_waitcnt vmcnt(7)
	v_sub_f32_e32 v119, v129, v61
	v_sub_f32_e32 v118, v128, v61
	v_sub_f32_e32 v121, v131, v61
	v_sub_f32_e32 v120, v130, v61
	v_pk_fma_f32 v[58:59], v[174:175], v[126:127], v[62:63]
	v_pk_fma_f32 v[56:57], v[172:173], v[124:125], v[142:143]
	global_load_dwordx4 v[60:63], v[146:147], off offset:16
	v_pk_fma_f32 v[66:67], v[66:67], v[120:121], v[150:151]
	v_pk_fma_f32 v[64:65], v[64:65], v[118:119], v[166:167]
	global_store_dwordx4 v[144:145], v[56:59], off offset:512
	global_store_dwordx4 v[144:145], v[64:67], off offset:528
	global_load_dwordx2 v[118:119], v[162:163], off offset:1024
	global_load_dwordx4 v[56:59], v[138:139], off offset:512
	v_lshl_add_u64 v[64:65], v[164:165], 0, s[4:5]
	global_load_dwordx4 v[64:67], v[64:65], off offset:16
	v_pk_fma_f32 v[134:135], v[28:29], v[76:77], v[110:111]
	s_waitcnt vmcnt(12)
	v_cndmask_b32_e64 v29, v114, 0, s[28:29]
	v_cndmask_b32_e64 v28, v115, 1.0, s[28:29]
	v_pk_fma_f32 v[124:125], v[34:35], v[108:109], v[102:103]
	v_pk_fma_f32 v[126:127], v[32:33], v[106:107], v[98:99]
	v_pk_fma_f32 v[32:33], v[42:43], v[78:79], v[112:113]
	v_pk_fma_f32 v[42:43], v[38:39], v[78:79], v[112:113]
	v_pk_fma_f32 v[128:129], v[36:37], v[76:77], v[110:111]
	v_pk_fma_f32 v[130:131], v[30:31], v[78:79], v[112:113]
	v_pk_mul_f32 v[34:35], v[90:91], v[28:29] op_sel_hi:[1,0]
	v_pk_mul_f32 v[30:31], v[94:95], v[28:29] op_sel_hi:[1,0]
	s_waitcnt vmcnt(11)
	v_sub_f32_e32 v37, v73, v29
	v_sub_f32_e32 v36, v72, v29
	v_sub_f32_e32 v39, v75, v29
	v_sub_f32_e32 v38, v74, v29
	v_pk_mul_f32 v[72:73], v[80:81], v[28:29] op_sel_hi:[1,0]
	v_pk_mul_f32 v[74:75], v[82:83], v[28:29] op_sel_hi:[1,0]
	s_waitcnt vmcnt(10)
; #define RES_LOADG(slot, g_) do { const int ro_ = ((g_) >> 2) * HALF + ((g_) & 3) * 16; \
;                 _Pragma("unroll") for (int n = 0; n < 2; ++n) xa[slot][n] = *(const f32x4*)(sl + rbase + (size_t)ro_ * 2048 + bj * HALF + 4 * n); \
;                 ms[slot] = *(const f2_t_*)(stp + 2 * (row0 + ro_)); } while (0)
;     __device__ __forceinline__ void operator()(const f32x4 (&acc)[2][2][4][2], const Unit& u, int wr, int wc, int fr, int fq) const {
;     ...
;             for (int gi = 0; gi < 8; ++gi) {
;                 const int ai = gi >> 2, m = gi & 3;
;                 if (gi + 2 < 8) RES_LOADG((gi + 2) % 3, gi + 2);
;                 asm volatile("" ::: "memory");
;                 float* rowp = xl + rbase + (size_t)(ai * HALF + m * 16) * 2048 + bj * HALF;
;                 const float mean = ln ? ms[gi % 3][0] : 0.f, rstd = ln ? ms[gi % 3][1] : 1.f;
; #pragma unroll
;                 for (int n = 0; n < 2; ++n) { const f32x4 t = ag[n] * rstd;
;                     *(f32x4*)(rowp + 4 * n) = (xa[gi % 3][n] - mean) * t + (ab[n] + mv[n] * acc[ai][bj][m][n]); }
;                 asm volatile("" ::: "memory");
;             }
	v_sub_f32_e32 v69, v69, v29
	v_sub_f32_e32 v68, v68, v29
	v_sub_f32_e32 v71, v71, v29
	v_sub_f32_e32 v70, v70, v29
	v_pk_fma_f32 v[30:31], v[30:31], v[38:39], v[50:51]
	v_pk_fma_f32 v[28:29], v[34:35], v[36:37], v[48:49]
	v_pk_fma_f32 v[34:35], v[74:75], v[70:71], v[32:33]
	v_pk_fma_f32 v[32:33], v[72:73], v[68:69], v[40:41]
	global_store_dwordx4 v[136:137], v[28:31], off offset:512
	global_store_dwordx4 v[136:137], v[32:35], off offset:528
	s_mov_b64 s[4:5], 0x120200
	v_lshl_add_u64 v[120:121], v[164:165], 0, s[4:5]
	global_load_dwordx4 v[28:31], v[132:133], off offset:512
	global_load_dwordx4 v[32:35], v[120:121], off offset:16
	global_load_dwordx2 v[68:69], v[162:163], off offset:1152
	s_mov_b64 s[4:5], 0x140200
	v_lshl_add_u64 v[122:123], v[164:165], 0, s[4:5]
	s_mov_b64 s[4:5], 0x160200
	s_waitcnt vmcnt(12)
	v_cndmask_b32_e64 v37, v116, 0, s[28:29]
	v_cndmask_b32_e64 v36, v117, 1.0, s[28:29]
	v_pk_mul_f32 v[40:41], v[90:91], v[36:37] op_sel_hi:[1,0]
	v_pk_mul_f32 v[38:39], v[94:95], v[36:37] op_sel_hi:[1,0]
	s_waitcnt vmcnt(11)
	v_sub_f32_e32 v49, v53, v37
	v_sub_f32_e32 v48, v52, v37
	v_sub_f32_e32 v51, v55, v37
	v_sub_f32_e32 v50, v54, v37
	v_pk_mul_f32 v[52:53], v[80:81], v[36:37] op_sel_hi:[1,0]
	v_pk_mul_f32 v[54:55], v[82:83], v[36:37] op_sel_hi:[1,0]
	v_pk_fma_f32 v[38:39], v[38:39], v[50:51], v[46:47]
	s_waitcnt vmcnt(10)
	v_sub_f32_e32 v61, v61, v37
	v_sub_f32_e32 v60, v60, v37
	v_sub_f32_e32 v63, v63, v37
	v_sub_f32_e32 v62, v62, v37
	v_pk_fma_f32 v[36:37], v[40:41], v[48:49], v[44:45]
	v_pk_fma_f32 v[42:43], v[54:55], v[62:63], v[42:43]
	v_pk_fma_f32 v[40:41], v[52:53], v[60:61], v[128:129]
	s_waitcnt vmcnt(7)
	v_cndmask_b32_e64 v45, v118, 0, s[28:29]
	v_cndmask_b32_e64 v44, v119, 1.0, s[28:29]
	global_store_dwordx4 v[104:105], v[36:39], off offset:512
	global_store_dwordx4 v[104:105], v[40:43], off offset:528
	s_waitcnt vmcnt(8)
	v_sub_f32_e32 v49, v57, v45
	v_sub_f32_e32 v48, v56, v45
	v_pk_mul_f32 v[40:41], v[90:91], v[44:45] op_sel_hi:[1,0]
	v_pk_mul_f32 v[42:43], v[94:95], v[44:45] op_sel_hi:[1,0]
	v_sub_f32_e32 v47, v59, v45
	v_sub_f32_e32 v46, v58, v45
	global_load_dwordx2 v[52:53], v[162:163], off offset:1280
	v_pk_mul_f32 v[54:55], v[80:81], v[44:45] op_sel_hi:[1,0]
	v_pk_mul_f32 v[50:51], v[82:83], v[44:45] op_sel_hi:[1,0]
	s_waitcnt vmcnt(8)
	v_sub_f32_e32 v57, v65, v45
	v_sub_f32_e32 v56, v64, v45
	v_sub_f32_e32 v59, v67, v45
	v_sub_f32_e32 v58, v66, v45
	v_pk_fma_f32 v[42:43], v[42:43], v[46:47], v[124:125]
	v_pk_fma_f32 v[40:41], v[40:41], v[48:49], v[126:127]
	global_load_dwordx4 v[36:39], v[100:101], off offset:512
	global_load_dwordx4 v[44:47], v[122:123], off offset:16
	v_pk_fma_f32 v[50:51], v[50:51], v[58:59], v[130:131]
	v_pk_fma_f32 v[48:49], v[54:55], v[56:57], v[134:135]
	global_store_dwordx4 v[96:97], v[40:43], off offset:512
	global_store_dwordx4 v[96:97], v[48:51], off offset:528
	global_load_dwordx2 v[54:55], v[162:163], off offset:1408
	global_load_dwordx4 v[40:43], v[92:93], off offset:512
	v_lshl_add_u64 v[48:49], v[164:165], 0, s[4:5]
	global_load_dwordx4 v[48:51], v[48:49], off offset:16
	v_pk_fma_f32 v[62:63], v[4:5], v[76:77], v[110:111]
	v_pk_fma_f32 v[56:57], v[10:11], v[78:79], v[112:113]
	v_pk_fma_f32 v[58:59], v[8:9], v[76:77], v[110:111]
	s_waitcnt vmcnt(10)
	v_cndmask_b32_e64 v5, v68, 0, s[28:29]
	v_cndmask_b32_e64 v4, v69, 1.0, s[28:29]
	v_pk_fma_f32 v[60:61], v[6:7], v[78:79], v[112:113]
	v_pk_mul_f32 v[8:9], v[90:91], v[4:5] op_sel_hi:[1,0]
	v_pk_mul_f32 v[6:7], v[94:95], v[4:5] op_sel_hi:[1,0]
	v_sub_f32_e32 v11, v29, v5
	v_sub_f32_e32 v10, v28, v5
	v_sub_f32_e32 v29, v31, v5
	v_sub_f32_e32 v28, v30, v5
	v_pk_mul_f32 v[30:31], v[80:81], v[4:5] op_sel_hi:[1,0]
	v_pk_mul_f32 v[64:65], v[82:83], v[4:5] op_sel_hi:[1,0]
	v_sub_f32_e32 v33, v33, v5
	v_sub_f32_e32 v32, v32, v5
	v_sub_f32_e32 v35, v35, v5
	v_sub_f32_e32 v34, v34, v5
	v_pk_fma_f32 v[6:7], v[6:7], v[28:29], v[26:27]
	v_pk_fma_f32 v[4:5], v[8:9], v[10:11], v[24:25]
	v_pk_fma_f32 v[10:11], v[64:65], v[34:35], v[14:15]
	v_pk_fma_f32 v[8:9], v[30:31], v[32:33], v[12:13]
	global_store_dwordx4 v[88:89], v[4:7], off offset:512
	global_store_dwordx4 v[88:89], v[8:11], off offset:528
	s_waitcnt vmcnt(9)
	v_cndmask_b32_e64 v5, v52, 0, s[28:29]
	v_cndmask_b32_e64 v4, v53, 1.0, s[28:29]
	v_pk_mul_f32 v[8:9], v[90:91], v[4:5] op_sel_hi:[1,0]
	v_pk_mul_f32 v[6:7], v[94:95], v[4:5] op_sel_hi:[1,0]
	v_pk_mul_f32 v[14:15], v[80:81], v[4:5] op_sel_hi:[1,0]
	v_pk_mul_f32 v[24:25], v[82:83], v[4:5] op_sel_hi:[1,0]
	s_waitcnt vmcnt(8)
	v_sub_f32_e32 v11, v37, v5
	v_sub_f32_e32 v10, v36, v5
	v_sub_f32_e32 v13, v39, v5
	v_sub_f32_e32 v12, v38, v5
	s_waitcnt vmcnt(7)
	v_sub_f32_e32 v27, v45, v5
	v_sub_f32_e32 v26, v44, v5
	v_sub_f32_e32 v29, v47, v5
	v_sub_f32_e32 v28, v46, v5
	v_pk_fma_f32 v[6:7], v[6:7], v[12:13], v[22:23]
	v_pk_fma_f32 v[4:5], v[8:9], v[10:11], v[20:21]
	v_pk_fma_f32 v[10:11], v[24:25], v[28:29], v[56:57]
	v_pk_fma_f32 v[8:9], v[14:15], v[26:27], v[58:59]
	s_waitcnt vmcnt(4)
	v_cndmask_b32_e64 v22, v54, 0, s[28:29]
	v_cndmask_b32_e64 v12, v55, 1.0, s[28:29]
	global_store_dwordx4 v[84:85], v[4:7], off offset:512
	global_store_dwordx4 v[84:85], v[8:11], off offset:528
	v_pk_mul_f32 v[14:15], v[80:81], v[12:13] op_sel_hi:[1,0]
	v_pk_mul_f32 v[4:5], v[90:91], v[12:13] op_sel_hi:[1,0]
	v_pk_mul_f32 v[6:7], v[94:95], v[12:13] op_sel_hi:[1,0]
	s_waitcnt vmcnt(5)
	v_sub_f32_e32 v9, v41, v22
	v_sub_f32_e32 v8, v40, v22
	v_sub_f32_e32 v11, v43, v22
	v_sub_f32_e32 v10, v42, v22
	v_pk_mul_f32 v[12:13], v[82:83], v[12:13] op_sel_hi:[1,0]
	s_waitcnt vmcnt(4)
	v_sub_f32_e32 v21, v49, v22
	v_sub_f32_e32 v20, v48, v22
	v_sub_f32_e32 v23, v51, v22
	v_sub_f32_e32 v22, v50, v22
	v_pk_fma_f32 v[6:7], v[6:7], v[10:11], v[18:19]
	v_pk_fma_f32 v[4:5], v[4:5], v[8:9], v[16:17]
	v_pk_fma_f32 v[10:11], v[12:13], v[22:23], v[60:61]
	v_pk_fma_f32 v[8:9], v[14:15], v[20:21], v[62:63]
	global_store_dwordx4 v[86:87], v[4:7], off offset:512
	global_store_dwordx4 v[86:87], v[8:11], off offset:528
	s_cbranch_vccnz .LBB0_308
	s_andn2_b64 vcc, exec, s[18:19]
	s_cbranch_vccnz .LBB0_307
	s_barrier
	s_branch .LBB0_307

; #define RES_LOADG(slot, g_) do { const int ro_ = ((g_) >> 2) * HALF + ((g_) & 3) * 16; \
;                 _Pragma("unroll") for (int n = 0; n < 2; ++n) xa[slot][n] = *(const f32x4*)(sl + rbase + (size_t)ro_ * 2048 + bj * HALF + 4 * n); \
;                 ms[slot] = *(const f2_t_*)(stp + 2 * (row0 + ro_)); } while (0)
;     __device__ __forceinline__ void operator()(const f32x4 (&acc)[2][2][4][2], const Unit& u, int wr, int wc, int fr, int fq) const {
;     ...
;         for (int bj = 0; bj < 2; ++bj) {
;             f32x4 mv[2], ag[2], ab[2];
; #pragma unroll
;             for (int n = 0; n < 2; ++n) { mv[n] = *(const f32x4*)(mp + col0 + bj * HALF + 4 * n) * coef;
;                 const f32x4 g4 = *(const f32x4*)(lg + col0 + bj * HALF + 4 * n), b4 = *(const f32x4*)(lb + col0 + bj * HALF + 4 * n);
;                 const f32x4 g4s = ln ? g4 : (f32x4){1.f, 1.f, 1.f, 1.f}, b4s = ln ? b4 : (f32x4){0.f, 0.f, 0.f, 0.f};
;                 ag[n] = g4s * al; ab[n] = b4s * al; }
;             f32x4 xa[3][2]; f2_t_ ms[3];
;     ...
;             RES_LOADG(0, 0); RES_LOADG(1, 1);
; #pragma unroll
;             for (int gi = 0; gi < 8; ++gi) {
;                 const int ai = gi >> 2, m = gi & 3;
;                 if (gi + 2 < 8) RES_LOADG((gi + 2) % 3, gi + 2);
;                 asm volatile("" ::: "memory");
;                 float* rowp = xl + rbase + (size_t)(ai * HALF + m * 16) * 2048 + bj * HALF;
;                 const float mean = ln ? ms[gi % 3][0] : 0.f, rstd = ln ? ms[gi % 3][1] : 1.f;
; #pragma unroll
;                 for (int n = 0; n < 2; ++n) { const f32x4 t = ag[n] * rstd;
;                     *(f32x4*)(rowp + 4 * n) = (xa[gi % 3][n] - mean) * t + (ab[n] + mv[n] * acc[ai][bj][m][n]); }
.LBB0_1076:
.LBB0_1078:
	s_waitcnt vmcnt(0)
	v_pk_mul_f32 v[144:145], v[144:145], s[40:41] op_sel_hi:[1,0]
	v_pk_mul_f32 v[140:141], v[140:141], s[40:41] op_sel_hi:[1,0]
	v_cndmask_b32_e64 v204, v144, 0, s[28:29]
	v_lshl_add_u32 v144, s73, 8, v216
	v_cndmask_b32_e64 v205, v145, 0, s[28:29]
	v_ashrrev_i32_e32 v145, 31, v144
	v_cndmask_b32_e64 v209, v141, 0, s[28:29]
	v_cndmask_b32_e64 v208, v140, 0, s[28:29]
	v_lshlrev_b64 v[140:141], 13, v[144:145]
	v_lshl_add_u64 v[140:141], s[8:9], 0, v[140:141]
	v_lshl_add_u64 v[172:173], v[148:149], 2, v[140:141]
	s_mov_b64 s[38:39], 0x20000
	v_pk_mul_f32 v[146:147], v[146:147], s[40:41] op_sel_hi:[1,0]
	v_lshl_add_u64 v[140:141], v[172:173], 0, s[38:39]
	s_mov_b32 s38, 0x20000
	v_cndmask_b32_e64 v206, v146, 0, s[28:29]
	v_lshlrev_b32_e32 v146, 1, v144
	v_add_co_u32_e32 v176, vcc, s38, v172
	v_cndmask_b32_e64 v207, v147, 0, s[28:29]
	v_ashrrev_i32_e32 v147, 31, v146
	v_addc_co_u32_e32 v177, vcc, 0, v173, vcc
	v_lshl_add_u64 v[170:171], v[146:147], 2, s[30:31]
	global_load_dwordx4 v[156:159], v[172:173], off offset:16
	global_load_dwordx4 v[220:223], v[172:173], off
	global_load_dwordx4 v[152:155], v[176:177], off
	global_load_dwordx4 v[148:151], v[140:141], off offset:16
	global_load_dwordx2 v[192:193], v[170:171], off
	global_load_dwordx2 v[214:215], v[170:171], off offset:128
	s_mov_b64 s[38:39], 0x40000
	v_lshl_add_u64 v[140:141], v[172:173], 0, s[38:39]
	s_mov_b32 s38, 0x40000
	v_pk_mul_f32 v[142:143], v[142:143], s[40:41] op_sel_hi:[1,0]
	v_add_co_u32_e32 v174, vcc, s38, v172
	v_pk_fma_f32 v[138:139], v[138:139], v[118:119], v[206:207]
	v_pk_fma_f32 v[136:137], v[136:137], v[116:117], v[204:205]
	v_cndmask_b32_e64 v211, v143, 0, s[28:29]
	v_cndmask_b32_e64 v210, v142, 0, s[28:29]
	v_addc_co_u32_e32 v175, vcc, 0, v173, vcc
	global_load_dwordx4 v[144:147], v[174:175], off
	s_nop 0
	global_load_dwordx4 v[140:143], v[140:141], off offset:16
	s_nop 0
	global_load_dwordx2 v[212:213], v[170:171], off offset:256
	v_pk_fma_f32 v[134:135], v[134:135], v[122:123], v[210:211]
	v_pk_fma_f32 v[132:133], v[132:133], v[120:121], v[208:209]
	s_mov_b64 s[38:39], 0x60000
	v_pk_fma_f32 v[130:131], v[130:131], v[118:119], v[206:207]
	v_pk_fma_f32 v[128:129], v[128:129], v[116:117], v[204:205]
	v_pk_fma_f32 v[126:127], v[126:127], v[122:123], v[210:211]
	v_pk_fma_f32 v[124:125], v[124:125], v[120:121], v[208:209]
	v_pk_fma_f32 v[114:115], v[114:115], v[118:119], v[206:207]
	v_pk_fma_f32 v[112:113], v[112:113], v[116:117], v[204:205]
	v_pk_fma_f32 v[110:111], v[110:111], v[122:123], v[210:211]
	v_pk_fma_f32 v[108:109], v[108:109], v[120:121], v[208:209]
	v_pk_fma_f32 v[106:107], v[106:107], v[118:119], v[206:207]
	v_pk_fma_f32 v[104:105], v[104:105], v[116:117], v[204:205]
	v_pk_fma_f32 v[102:103], v[102:103], v[122:123], v[210:211]
	v_pk_fma_f32 v[100:101], v[100:101], v[120:121], v[208:209]
	v_pk_fma_f32 v[98:99], v[98:99], v[118:119], v[206:207]
	v_pk_fma_f32 v[96:97], v[96:97], v[116:117], v[204:205]
	v_pk_fma_f32 v[94:95], v[94:95], v[122:123], v[210:211]
	v_pk_fma_f32 v[92:93], v[92:93], v[120:121], v[208:209]
	v_pk_fma_f32 v[90:91], v[90:91], v[118:119], v[206:207]
	v_pk_fma_f32 v[88:89], v[88:89], v[116:117], v[204:205]
	v_pk_fma_f32 v[86:87], v[86:87], v[122:123], v[210:211]
	v_pk_fma_f32 v[84:85], v[84:85], v[120:121], v[208:209]
	v_pk_fma_f32 v[82:83], v[82:83], v[118:119], v[206:207]
	v_pk_fma_f32 v[80:81], v[80:81], v[116:117], v[204:205]
	v_pk_fma_f32 v[78:79], v[78:79], v[122:123], v[210:211]
	v_pk_fma_f32 v[76:77], v[76:77], v[120:121], v[208:209]
	v_pk_fma_f32 v[74:75], v[74:75], v[118:119], v[206:207]
	v_pk_fma_f32 v[72:73], v[72:73], v[116:117], v[204:205]
	v_pk_fma_f32 v[70:71], v[70:71], v[122:123], v[210:211]
	v_pk_fma_f32 v[68:69], v[68:69], v[120:121], v[208:209]
	s_waitcnt vmcnt(4)
	v_cndmask_b32_e64 v228, v192, 0, s[28:29]
	v_cndmask_b32_e64 v192, v193, 1.0, s[28:29]
	v_pk_mul_f32 v[196:197], v[188:189], v[192:193] op_sel_hi:[1,0]
	v_pk_mul_f32 v[198:199], v[186:187], v[192:193] op_sel_hi:[1,0]
	v_sub_f32_e32 v201, v221, v228
	v_sub_f32_e32 v200, v220, v228
	v_sub_f32_e32 v203, v223, v228
	v_sub_f32_e32 v202, v222, v228
	v_pk_fma_f32 v[138:139], v[198:199], v[202:203], v[138:139]
	v_pk_fma_f32 v[136:137], v[196:197], v[200:201], v[136:137]
	global_store_dwordx4 v[172:173], v[136:139], off
	v_sub_f32_e32 v157, v157, v228
	v_sub_f32_e32 v156, v156, v228
	v_pk_mul_f32 v[136:137], v[184:185], v[192:193] op_sel_hi:[1,0]
	v_pk_mul_f32 v[138:139], v[190:191], v[192:193] op_sel_hi:[1,0]
	v_sub_f32_e32 v159, v159, v228
	v_sub_f32_e32 v158, v158, v228
	v_pk_fma_f32 v[134:135], v[138:139], v[158:159], v[134:135]
	v_pk_fma_f32 v[132:133], v[136:137], v[156:157], v[132:133]
	global_store_dwordx4 v[172:173], v[132:135], off offset:16
	s_waitcnt vmcnt(5)
	v_cndmask_b32_e64 v193, v214, 0, s[28:29]
	v_cndmask_b32_e64 v192, v215, 1.0, s[28:29]
	v_lshl_add_u64 v[132:133], v[172:173], 0, s[38:39]
	s_mov_b32 s38, 0x60000
	v_add_co_u32_e32 v156, vcc, s38, v172
	v_pk_mul_f32 v[196:197], v[188:189], v[192:193] op_sel_hi:[1,0]
	v_pk_mul_f32 v[198:199], v[186:187], v[192:193] op_sel_hi:[1,0]
	v_sub_f32_e32 v153, v153, v193
	v_sub_f32_e32 v152, v152, v193
	v_sub_f32_e32 v155, v155, v193
	v_sub_f32_e32 v154, v154, v193
	v_addc_co_u32_e32 v157, vcc, 0, v173, vcc
	v_pk_fma_f32 v[130:131], v[198:199], v[154:155], v[130:131]
	v_pk_fma_f32 v[128:129], v[196:197], v[152:153], v[128:129]
	global_load_dwordx4 v[136:139], v[156:157], off
	s_nop 0
	global_load_dwordx4 v[132:135], v[132:133], off offset:16
	s_nop 0
	global_load_dwordx2 v[158:159], v[170:171], off offset:384
	global_store_dwordx4 v[176:177], v[128:131], off
	v_pk_mul_f32 v[152:153], v[190:191], v[192:193] op_sel_hi:[1,0]
	s_mov_b64 s[38:39], 0x100000
	v_pk_mul_f32 v[128:129], v[184:185], v[192:193] op_sel_hi:[1,0]
	v_sub_f32_e32 v131, v149, v193
	v_sub_f32_e32 v130, v148, v193
	v_sub_f32_e32 v149, v151, v193
	v_sub_f32_e32 v148, v150, v193
	v_pk_fma_f32 v[126:127], v[152:153], v[148:149], v[126:127]
	v_pk_fma_f32 v[124:125], v[128:129], v[130:131], v[124:125]
	global_store_dwordx4 v[176:177], v[124:127], off offset:16
	s_waitcnt vmcnt(7)
; #define RES_LOADG(slot, g_) do { const int ro_ = ((g_) >> 2) * HALF + ((g_) & 3) * 16; \
;                 _Pragma("unroll") for (int n = 0; n < 2; ++n) xa[slot][n] = *(const f32x4*)(sl + rbase + (size_t)ro_ * 2048 + bj * HALF + 4 * n); \
;                 ms[slot] = *(const f2_t_*)(stp + 2 * (row0 + ro_)); } while (0)
;     __device__ __forceinline__ void operator()(const f32x4 (&acc)[2][2][4][2], const Unit& u, int wr, int wc, int fr, int fq) const {
;     ...
;             for (int gi = 0; gi < 8; ++gi) {
;                 const int ai = gi >> 2, m = gi & 3;
;                 if (gi + 2 < 8) RES_LOADG((gi + 2) % 3, gi + 2);
;                 asm volatile("" ::: "memory");
;                 float* rowp = xl + rbase + (size_t)(ai * HALF + m * 16) * 2048 + bj * HALF;
;                 const float mean = ln ? ms[gi % 3][0] : 0.f, rstd = ln ? ms[gi % 3][1] : 1.f;
; #pragma unroll
;                 for (int n = 0; n < 2; ++n) { const f32x4 t = ag[n] * rstd;
;                     *(f32x4*)(rowp + 4 * n) = (xa[gi % 3][n] - mean) * t + (ab[n] + mv[n] * acc[ai][bj][m][n]); }
;                 asm volatile("" ::: "memory");
	v_cndmask_b32_e64 v153, v212, 0, s[28:29]
	v_cndmask_b32_e64 v152, v213, 1.0, s[28:29]
	v_lshl_add_u64 v[124:125], v[172:173], 0, s[38:39]
	s_mov_b32 s38, 0x100000
	v_add_co_u32_e32 v148, vcc, s38, v172
	v_pk_mul_f32 v[154:155], v[188:189], v[152:153] op_sel_hi:[1,0]
	s_nop 0
	v_addc_co_u32_e32 v149, vcc, 0, v173, vcc
	global_load_dwordx4 v[128:131], v[148:149], off
	s_nop 0
	global_load_dwordx4 v[124:127], v[124:125], off offset:16
	s_nop 0
	global_load_dwordx2 v[150:151], v[170:171], off offset:1024
	v_pk_mul_f32 v[192:193], v[186:187], v[152:153] op_sel_hi:[1,0]
	v_sub_f32_e32 v145, v145, v153
	v_sub_f32_e32 v144, v144, v153
	v_sub_f32_e32 v147, v147, v153
	v_sub_f32_e32 v146, v146, v153
	v_pk_fma_f32 v[114:115], v[192:193], v[146:147], v[114:115]
	v_pk_fma_f32 v[112:113], v[154:155], v[144:145], v[112:113]
	global_store_dwordx4 v[174:175], v[112:115], off
	v_sub_f32_e32 v141, v141, v153
	v_sub_f32_e32 v140, v140, v153
	v_pk_mul_f32 v[112:113], v[184:185], v[152:153] op_sel_hi:[1,0]
	v_pk_mul_f32 v[114:115], v[190:191], v[152:153] op_sel_hi:[1,0]
	v_sub_f32_e32 v143, v143, v153
	v_sub_f32_e32 v142, v142, v153
	v_pk_fma_f32 v[110:111], v[114:115], v[142:143], v[110:111]
	v_pk_fma_f32 v[108:109], v[112:113], v[140:141], v[108:109]
	s_mov_b64 s[38:39], 0x120000
	global_store_dwordx4 v[174:175], v[108:111], off offset:16
	s_waitcnt vmcnt(7)
	v_cndmask_b32_e64 v145, v158, 0, s[28:29]
	v_lshl_add_u64 v[108:109], v[172:173], 0, s[38:39]
	s_mov_b32 s38, 0x120000
	v_cndmask_b32_e64 v144, v159, 1.0, s[28:29]
	v_add_co_u32_e32 v140, vcc, s38, v172
	v_pk_mul_f32 v[146:147], v[188:189], v[144:145] op_sel_hi:[1,0]
	v_pk_mul_f32 v[152:153], v[186:187], v[144:145] op_sel_hi:[1,0]
	v_sub_f32_e32 v137, v137, v145
	v_sub_f32_e32 v136, v136, v145
	v_sub_f32_e32 v139, v139, v145
	v_sub_f32_e32 v138, v138, v145
	v_addc_co_u32_e32 v141, vcc, 0, v173, vcc
	v_pk_fma_f32 v[106:107], v[152:153], v[138:139], v[106:107]
	v_pk_fma_f32 v[104:105], v[146:147], v[136:137], v[104:105]
	global_load_dwordx4 v[112:115], v[140:141], off
	s_nop 0
	global_load_dwordx4 v[108:111], v[108:109], off offset:16
	s_nop 0
	global_load_dwordx2 v[142:143], v[170:171], off offset:1152
	global_store_dwordx4 v[156:157], v[104:107], off
	v_sub_f32_e32 v133, v133, v145
	v_sub_f32_e32 v132, v132, v145
	v_pk_mul_f32 v[104:105], v[184:185], v[144:145] op_sel_hi:[1,0]
	v_pk_mul_f32 v[106:107], v[190:191], v[144:145] op_sel_hi:[1,0]
	v_sub_f32_e32 v135, v135, v145
	v_sub_f32_e32 v134, v134, v145
	v_pk_fma_f32 v[102:103], v[106:107], v[134:135], v[102:103]
	v_pk_fma_f32 v[100:101], v[104:105], v[132:133], v[100:101]
	s_mov_b64 s[38:39], 0x140000
	global_store_dwordx4 v[156:157], v[100:103], off offset:16
	s_waitcnt vmcnt(7)
	v_cndmask_b32_e64 v146, v150, 0, s[28:29]
	v_cndmask_b32_e64 v106, v151, 1.0, s[28:29]
	v_lshl_add_u64 v[100:101], v[172:173], 0, s[38:39]
	s_mov_b32 s38, 0x140000
	v_add_co_u32_e32 v104, vcc, s38, v172
	v_pk_mul_f32 v[138:139], v[188:189], v[106:107] op_sel_hi:[1,0]
	v_pk_mul_f32 v[144:145], v[186:187], v[106:107] op_sel_hi:[1,0]
	v_sub_f32_e32 v129, v129, v146
	v_sub_f32_e32 v128, v128, v146
	v_sub_f32_e32 v131, v131, v146
	v_sub_f32_e32 v130, v130, v146
	v_addc_co_u32_e32 v105, vcc, 0, v173, vcc
	v_pk_fma_f32 v[98:99], v[144:145], v[130:131], v[98:99]
	v_pk_fma_f32 v[96:97], v[138:139], v[128:129], v[96:97]
	global_load_dwordx4 v[132:135], v[104:105], off
	s_nop 0
	global_load_dwordx4 v[100:103], v[100:101], off offset:16
	s_nop 0
	global_load_dwordx2 v[136:137], v[170:171], off offset:1280
	global_store_dwordx4 v[148:149], v[96:99], off
	s_mov_b64 s[38:39], 0x160000
	s_nop 0
	v_pk_mul_f32 v[96:97], v[184:185], v[106:107] op_sel_hi:[1,0]
	v_pk_mul_f32 v[98:99], v[190:191], v[106:107] op_sel_hi:[1,0]
	v_sub_f32_e32 v107, v125, v146
	v_sub_f32_e32 v106, v124, v146
	v_sub_f32_e32 v125, v127, v146
	v_sub_f32_e32 v124, v126, v146
	v_pk_fma_f32 v[94:95], v[98:99], v[124:125], v[94:95]
	v_pk_fma_f32 v[92:93], v[96:97], v[106:107], v[92:93]
	global_store_dwordx4 v[148:149], v[92:95], off offset:16
	s_waitcnt vmcnt(7)
; #define RES_LOADG(slot, g_) do { const int ro_ = ((g_) >> 2) * HALF + ((g_) & 3) * 16; \
;                 _Pragma("unroll") for (int n = 0; n < 2; ++n) xa[slot][n] = *(const f32x4*)(sl + rbase + (size_t)ro_ * 2048 + bj * HALF + 4 * n); \
;                 ms[slot] = *(const f2_t_*)(stp + 2 * (row0 + ro_)); } while (0)
;     __device__ __forceinline__ void operator()(const f32x4 (&acc)[2][2][4][2], const Unit& u, int wr, int wc, int fr, int fq) const {
;     ...
;             for (int n = 0; n < 2; ++n) { mv[n] = *(const f32x4*)(mp + col0 + bj * HALF + 4 * n) * coef;
;                 const f32x4 g4 = *(const f32x4*)(lg + col0 + bj * HALF + 4 * n), b4 = *(const f32x4*)(lb + col0 + bj * HALF + 4 * n);
;                 const f32x4 g4s = ln ? g4 : (f32x4){1.f, 1.f, 1.f, 1.f}, b4s = ln ? b4 : (f32x4){0.f, 0.f, 0.f, 0.f};
;                 ag[n] = g4s * al; ab[n] = b4s * al; }
;     ...
;             for (int gi = 0; gi < 8; ++gi) {
;                 const int ai = gi >> 2, m = gi & 3;
;                 if (gi + 2 < 8) RES_LOADG((gi + 2) % 3, gi + 2);
;                 asm volatile("" ::: "memory");
;                 float* rowp = xl + rbase + (size_t)(ai * HALF + m * 16) * 2048 + bj * HALF;
;                 const float mean = ln ? ms[gi % 3][0] : 0.f, rstd = ln ? ms[gi % 3][1] : 1.f;
; #pragma unroll
;                 for (int n = 0; n < 2; ++n) { const f32x4 t = ag[n] * rstd;
;                     *(f32x4*)(rowp + 4 * n) = (xa[gi % 3][n] - mean) * t + (ab[n] + mv[n] * acc[ai][bj][m][n]); }
;                 asm volatile("" ::: "memory");
	v_cndmask_b32_e64 v127, v142, 0, s[28:29]
	v_lshl_add_u64 v[92:93], v[172:173], 0, s[38:39]
	s_mov_b32 s38, 0x160000
	v_add_co_u32_e32 v106, vcc, s38, v172
	v_cndmask_b32_e64 v126, v143, 1.0, s[28:29]
	s_nop 0
	v_addc_co_u32_e32 v107, vcc, 0, v173, vcc
	global_load_dwordx4 v[96:99], v[106:107], off
	s_nop 0
	global_load_dwordx4 v[92:95], v[92:93], off offset:16
	s_nop 0
	global_load_dwordx2 v[124:125], v[170:171], off offset:1408
	v_pk_mul_f32 v[128:129], v[188:189], v[126:127] op_sel_hi:[1,0]
	v_pk_mul_f32 v[130:131], v[186:187], v[126:127] op_sel_hi:[1,0]
	v_sub_f32_e32 v113, v113, v127
	v_sub_f32_e32 v112, v112, v127
	v_sub_f32_e32 v115, v115, v127
	v_sub_f32_e32 v114, v114, v127
	v_pk_fma_f32 v[90:91], v[130:131], v[114:115], v[90:91]
	v_pk_fma_f32 v[88:89], v[128:129], v[112:113], v[88:89]
	global_store_dwordx4 v[140:141], v[88:91], off
	v_sub_f32_e32 v109, v109, v127
	v_sub_f32_e32 v108, v108, v127
	v_pk_mul_f32 v[88:89], v[184:185], v[126:127] op_sel_hi:[1,0]
	v_pk_mul_f32 v[90:91], v[190:191], v[126:127] op_sel_hi:[1,0]
	v_sub_f32_e32 v111, v111, v127
	v_sub_f32_e32 v110, v110, v127
	v_pk_fma_f32 v[86:87], v[90:91], v[110:111], v[86:87]
	v_pk_fma_f32 v[84:85], v[88:89], v[108:109], v[84:85]
	global_store_dwordx4 v[140:141], v[84:87], off offset:16
	s_waitcnt vmcnt(7)
	v_cndmask_b32_e64 v110, v136, 0, s[28:29]
	v_sub_f32_e32 v91, v133, v110
	v_cndmask_b32_e64 v84, v137, 1.0, s[28:29]
	v_pk_mul_f32 v[86:87], v[188:189], v[84:85] op_sel_hi:[1,0]
	v_pk_mul_f32 v[88:89], v[186:187], v[84:85] op_sel_hi:[1,0]
	v_sub_f32_e32 v90, v132, v110
	v_sub_f32_e32 v109, v135, v110
	v_sub_f32_e32 v108, v134, v110
	v_pk_fma_f32 v[82:83], v[88:89], v[108:109], v[82:83]
	v_pk_fma_f32 v[80:81], v[86:87], v[90:91], v[80:81]
	global_store_dwordx4 v[104:105], v[80:83], off
	v_sub_f32_e32 v87, v103, v110
	v_sub_f32_e32 v86, v102, v110
	v_pk_mul_f32 v[80:81], v[184:185], v[84:85] op_sel_hi:[1,0]
	v_pk_mul_f32 v[82:83], v[190:191], v[84:85] op_sel_hi:[1,0]
	v_sub_f32_e32 v85, v101, v110
	v_sub_f32_e32 v84, v100, v110
	v_pk_fma_f32 v[78:79], v[82:83], v[86:87], v[78:79]
	v_pk_fma_f32 v[76:77], v[80:81], v[84:85], v[76:77]
	global_store_dwordx4 v[104:105], v[76:79], off offset:16
	s_and_b64 vcc, exec, s[4:5]
	v_mov_b32_e32 v87, 0x3fb504f3
	s_waitcnt vmcnt(4)
	v_cndmask_b32_e64 v86, v124, 0, s[28:29]
	v_cndmask_b32_e64 v76, v125, 1.0, s[28:29]
	v_pk_mul_f32 v[78:79], v[188:189], v[76:77] op_sel_hi:[1,0]
	v_pk_mul_f32 v[80:81], v[186:187], v[76:77] op_sel_hi:[1,0]
	v_sub_f32_e32 v83, v97, v86
	v_sub_f32_e32 v82, v96, v86
	v_sub_f32_e32 v85, v99, v86
	v_sub_f32_e32 v84, v98, v86
	v_pk_fma_f32 v[74:75], v[80:81], v[84:85], v[74:75]
	v_pk_fma_f32 v[72:73], v[78:79], v[82:83], v[72:73]
	global_store_dwordx4 v[106:107], v[72:75], off
	v_sub_f32_e32 v79, v95, v86
	v_sub_f32_e32 v78, v94, v86
	v_pk_mul_f32 v[72:73], v[184:185], v[76:77] op_sel_hi:[1,0]
	v_pk_mul_f32 v[74:75], v[190:191], v[76:77] op_sel_hi:[1,0]
	v_sub_f32_e32 v77, v93, v86
	v_sub_f32_e32 v76, v92, v86
	v_pk_fma_f32 v[70:71], v[74:75], v[78:79], v[70:71]
	v_pk_fma_f32 v[68:69], v[72:73], v[76:77], v[68:69]
	global_store_dwordx4 v[106:107], v[68:71], off offset:16
	global_load_dwordx4 v[68:71], v[182:183], off offset:512
	global_load_dwordx4 v[80:83], v[178:179], off offset:512
	v_mov_b32_e32 v84, 0x3fb504f3
	v_mov_b32_e32 v85, 0x3fb504f3
	v_mov_b32_e32 v86, 0x3fb504f3
	global_load_dwordx4 v[72:75], v[182:183], off offset:528
	global_load_dwordx4 v[76:79], v[178:179], off offset:528
	s_cbranch_vccnz .LBB0_1082
	global_load_dwordx4 v[244:247], v[180:181], off offset:512
	global_load_dwordx4 v[92:95], v[180:181], off offset:528
	s_waitcnt vmcnt(0)
	v_pk_mul_f32 v[86:87], v[246:247], s[40:41] op_sel_hi:[1,0]
	v_pk_mul_f32 v[84:85], v[244:245], s[40:41] op_sel_hi:[1,0]
	v_pk_mul_f32 v[90:91], v[82:83], s[40:41] op_sel_hi:[1,0]
	v_pk_mul_f32 v[88:89], v[80:81], s[40:41] op_sel_hi:[1,0]
	v_pk_mul_f32 v[82:83], v[94:95], s[40:41] op_sel_hi:[1,0]
	v_pk_mul_f32 v[80:81], v[92:93], s[40:41] op_sel_hi:[1,0]
	s_branch .LBB0_1083

; #define RES_LOADG(slot, g_) do { const int ro_ = ((g_) >> 2) * HALF + ((g_) & 3) * 16; \
;                 _Pragma("unroll") for (int n = 0; n < 2; ++n) xa[slot][n] = *(const f32x4*)(sl + rbase + (size_t)ro_ * 2048 + bj * HALF + 4 * n); \
;                 ms[slot] = *(const f2_t_*)(stp + 2 * (row0 + ro_)); } while (0)
;     __device__ __forceinline__ void operator()(const f32x4 (&acc)[2][2][4][2], const Unit& u, int wr, int wc, int fr, int fq) const {
;     ...
;         for (int bj = 0; bj < 2; ++bj) {
;             f32x4 mv[2], ag[2], ab[2];
; #pragma unroll
;             for (int n = 0; n < 2; ++n) { mv[n] = *(const f32x4*)(mp + col0 + bj * HALF + 4 * n) * coef;
;                 const f32x4 g4 = *(const f32x4*)(lg + col0 + bj * HALF + 4 * n), b4 = *(const f32x4*)(lb + col0 + bj * HALF + 4 * n);
;                 const f32x4 g4s = ln ? g4 : (f32x4){1.f, 1.f, 1.f, 1.f}, b4s = ln ? b4 : (f32x4){0.f, 0.f, 0.f, 0.f};
;                 ag[n] = g4s * al; ab[n] = b4s * al; }
;             f32x4 xa[3][2]; f2_t_ ms[3];
;     ...
;             RES_LOADG(0, 0); RES_LOADG(1, 1);
; #pragma unroll
;             for (int gi = 0; gi < 8; ++gi) {
;                 const int ai = gi >> 2, m = gi & 3;
;                 if (gi + 2 < 8) RES_LOADG((gi + 2) % 3, gi + 2);
;                 asm volatile("" ::: "memory");
;                 float* rowp = xl + rbase + (size_t)(ai * HALF + m * 16) * 2048 + bj * HALF;
;                 const float mean = ln ? ms[gi % 3][0] : 0.f, rstd = ln ? ms[gi % 3][1] : 1.f;
; #pragma unroll
;                 for (int n = 0; n < 2; ++n) { const f32x4 t = ag[n] * rstd;
;                     *(f32x4*)(rowp + 4 * n) = (xa[gi % 3][n] - mean) * t + (ab[n] + mv[n] * acc[ai][bj][m][n]); }
;                 asm volatile("" ::: "memory");
;             }
.LBB0_1083:
	global_load_dwordx2 v[102:103], v[170:171], off
	global_load_dwordx2 v[116:117], v[170:171], off offset:128
	global_load_dwordx4 v[94:97], v[172:173], off offset:512
	global_load_dwordx4 v[98:101], v[172:173], off offset:528
	global_load_dwordx4 v[108:111], v[176:177], off offset:512
	s_mov_b64 s[4:5], 0x20200
	v_lshl_add_u64 v[92:93], v[172:173], 0, s[4:5]
	global_load_dwordx4 v[112:115], v[92:93], off offset:16
	v_pk_mul_f32 v[76:77], v[76:77], s[40:41] op_sel_hi:[1,0]
	v_pk_mul_f32 v[78:79], v[78:79], s[40:41] op_sel_hi:[1,0]
	s_mov_b64 s[4:5], 0x40200
	v_cndmask_b32_e64 v77, v77, 0, s[28:29]
	v_cndmask_b32_e64 v76, v76, 0, s[28:29]
	v_lshl_add_u64 v[118:119], v[172:173], 0, s[4:5]
	v_cndmask_b32_e64 v79, v79, 0, s[28:29]
	v_cndmask_b32_e64 v78, v78, 0, s[28:29]
	v_pk_fma_f32 v[130:131], v[52:53], v[72:73], v[76:77]
	global_load_dwordx2 v[92:93], v[170:171], off offset:256
	v_pk_fma_f32 v[120:121], v[66:67], v[70:71], v[90:91]
	v_pk_fma_f32 v[122:123], v[64:65], v[68:69], v[88:89]
	v_pk_fma_f32 v[126:127], v[62:63], v[70:71], v[90:91]
	v_pk_fma_f32 v[128:129], v[60:61], v[68:69], v[88:89]
	global_load_dwordx4 v[64:67], v[174:175], off offset:512
	global_load_dwordx4 v[60:63], v[118:119], off offset:16
	v_pk_fma_f32 v[118:119], v[54:55], v[74:75], v[78:79]
	v_pk_fma_f32 v[58:59], v[58:59], v[74:75], v[78:79]
	v_pk_fma_f32 v[56:57], v[56:57], v[72:73], v[76:77]
	s_mov_b64 s[4:5], 0x60200
	v_lshl_add_u64 v[124:125], v[172:173], 0, s[4:5]
	s_mov_b64 s[4:5], 0x100200
	v_pk_fma_f32 v[50:51], v[50:51], v[70:71], v[90:91]
	v_pk_fma_f32 v[48:49], v[48:49], v[68:69], v[88:89]
	v_pk_fma_f32 v[40:41], v[40:41], v[72:73], v[76:77]
	v_pk_fma_f32 v[46:47], v[46:47], v[70:71], v[90:91]
	v_pk_fma_f32 v[44:45], v[44:45], v[68:69], v[88:89]
	v_pk_fma_f32 v[26:27], v[26:27], v[70:71], v[90:91]
	v_pk_fma_f32 v[24:25], v[24:25], v[68:69], v[88:89]
	v_pk_fma_f32 v[14:15], v[14:15], v[74:75], v[78:79]
	v_pk_fma_f32 v[12:13], v[12:13], v[72:73], v[76:77]
	v_pk_fma_f32 v[22:23], v[22:23], v[70:71], v[90:91]
	v_pk_fma_f32 v[20:21], v[20:21], v[68:69], v[88:89]
	v_pk_fma_f32 v[18:19], v[18:19], v[70:71], v[90:91]
	v_pk_fma_f32 v[16:17], v[16:17], v[68:69], v[88:89]
	s_and_b64 vcc, exec, s[2:3]
	s_mov_b64 s[2:3], -1
	s_waitcnt vmcnt(8)
	v_cndmask_b32_e64 v53, v102, 0, s[28:29]
	v_cndmask_b32_e64 v52, v103, 1.0, s[28:29]
	s_waitcnt vmcnt(7)
	v_cndmask_b32_e64 v142, v116, 0, s[28:29]
	v_cndmask_b32_e64 v102, v117, 1.0, s[28:29]
	v_pk_mul_f32 v[116:117], v[84:85], v[52:53] op_sel_hi:[1,0]
	v_pk_mul_f32 v[54:55], v[86:87], v[52:53] op_sel_hi:[1,0]
	s_waitcnt vmcnt(6)
	v_sub_f32_e32 v95, v95, v53
	v_sub_f32_e32 v94, v94, v53
	v_sub_f32_e32 v97, v97, v53
	v_sub_f32_e32 v96, v96, v53
	v_pk_mul_f32 v[132:133], v[80:81], v[52:53] op_sel_hi:[1,0]
	v_pk_mul_f32 v[134:135], v[82:83], v[52:53] op_sel_hi:[1,0]
	s_waitcnt vmcnt(5)
	v_sub_f32_e32 v99, v99, v53
	v_sub_f32_e32 v98, v98, v53
	v_sub_f32_e32 v101, v101, v53
	v_sub_f32_e32 v100, v100, v53
	v_pk_fma_f32 v[54:55], v[54:55], v[96:97], v[120:121]
	v_pk_fma_f32 v[52:53], v[116:117], v[94:95], v[122:123]
	v_pk_fma_f32 v[58:59], v[134:135], v[100:101], v[58:59]
	v_pk_fma_f32 v[56:57], v[132:133], v[98:99], v[56:57]
	global_store_dwordx4 v[172:173], v[52:55], off offset:512
	global_store_dwordx4 v[172:173], v[56:59], off offset:528
	v_pk_mul_f32 v[136:137], v[84:85], v[102:103] op_sel_hi:[1,0]
	v_pk_mul_f32 v[138:139], v[86:87], v[102:103] op_sel_hi:[1,0]
	s_waitcnt vmcnt(6)
	v_sub_f32_e32 v109, v109, v142
	v_sub_f32_e32 v108, v108, v142
	v_sub_f32_e32 v111, v111, v142
	global_load_dwordx2 v[116:117], v[170:171], off offset:384
	v_sub_f32_e32 v110, v110, v142
	v_pk_mul_f32 v[98:99], v[80:81], v[102:103] op_sel_hi:[1,0]
	v_pk_mul_f32 v[100:101], v[82:83], v[102:103] op_sel_hi:[1,0]
	global_load_dwordx4 v[52:55], v[156:157], off offset:512
	global_load_dwordx4 v[94:97], v[124:125], off offset:16
	s_waitcnt vmcnt(8)
	v_sub_f32_e32 v103, v113, v142
	v_sub_f32_e32 v102, v112, v142
	v_sub_f32_e32 v113, v115, v142
	v_sub_f32_e32 v112, v114, v142
	v_pk_fma_f32 v[58:59], v[138:139], v[110:111], v[126:127]
	v_pk_fma_f32 v[56:57], v[136:137], v[108:109], v[128:129]
	v_pk_fma_f32 v[100:101], v[100:101], v[112:113], v[118:119]
	v_pk_fma_f32 v[98:99], v[98:99], v[102:103], v[130:131]
	global_store_dwordx4 v[176:177], v[56:59], off offset:512
	global_store_dwordx4 v[176:177], v[98:101], off offset:528
	global_load_dwordx2 v[102:103], v[170:171], off offset:1024
	global_load_dwordx4 v[56:59], v[148:149], off offset:512
	v_lshl_add_u64 v[98:99], v[172:173], 0, s[4:5]
	global_load_dwordx4 v[98:101], v[98:99], off offset:16
	v_pk_fma_f32 v[122:123], v[28:29], v[72:73], v[76:77]
	s_waitcnt vmcnt(12)
	v_cndmask_b32_e64 v29, v92, 0, s[28:29]
	v_cndmask_b32_e64 v28, v93, 1.0, s[28:29]
	v_pk_fma_f32 v[112:113], v[34:35], v[70:71], v[90:91]
	v_pk_fma_f32 v[114:115], v[32:33], v[68:69], v[88:89]
	v_pk_fma_f32 v[32:33], v[42:43], v[74:75], v[78:79]
	v_pk_fma_f32 v[42:43], v[38:39], v[74:75], v[78:79]
	v_pk_fma_f32 v[118:119], v[36:37], v[72:73], v[76:77]
	v_pk_fma_f32 v[120:121], v[30:31], v[74:75], v[78:79]
	v_pk_mul_f32 v[34:35], v[84:85], v[28:29] op_sel_hi:[1,0]
	v_pk_mul_f32 v[30:31], v[86:87], v[28:29] op_sel_hi:[1,0]
	s_waitcnt vmcnt(11)
	v_sub_f32_e32 v37, v65, v29
	v_sub_f32_e32 v36, v64, v29
	v_sub_f32_e32 v39, v67, v29
	v_sub_f32_e32 v38, v66, v29
	v_pk_mul_f32 v[64:65], v[80:81], v[28:29] op_sel_hi:[1,0]
	v_pk_mul_f32 v[66:67], v[82:83], v[28:29] op_sel_hi:[1,0]
	s_waitcnt vmcnt(10)
; #define RES_LOADG(slot, g_) do { const int ro_ = ((g_) >> 2) * HALF + ((g_) & 3) * 16; \
;                 _Pragma("unroll") for (int n = 0; n < 2; ++n) xa[slot][n] = *(const f32x4*)(sl + rbase + (size_t)ro_ * 2048 + bj * HALF + 4 * n); \
;                 ms[slot] = *(const f2_t_*)(stp + 2 * (row0 + ro_)); } while (0)
;     __device__ __forceinline__ void operator()(const f32x4 (&acc)[2][2][4][2], const Unit& u, int wr, int wc, int fr, int fq) const {
;     ...
;             for (int gi = 0; gi < 8; ++gi) {
;                 const int ai = gi >> 2, m = gi & 3;
;                 if (gi + 2 < 8) RES_LOADG((gi + 2) % 3, gi + 2);
;                 asm volatile("" ::: "memory");
;                 float* rowp = xl + rbase + (size_t)(ai * HALF + m * 16) * 2048 + bj * HALF;
;                 const float mean = ln ? ms[gi % 3][0] : 0.f, rstd = ln ? ms[gi % 3][1] : 1.f;
; #pragma unroll
;                 for (int n = 0; n < 2; ++n) { const f32x4 t = ag[n] * rstd;
;                     *(f32x4*)(rowp + 4 * n) = (xa[gi % 3][n] - mean) * t + (ab[n] + mv[n] * acc[ai][bj][m][n]); }
;                 asm volatile("" ::: "memory");
;             }
	v_sub_f32_e32 v61, v61, v29
	v_sub_f32_e32 v60, v60, v29
	v_sub_f32_e32 v63, v63, v29
	v_sub_f32_e32 v62, v62, v29
	v_pk_fma_f32 v[30:31], v[30:31], v[38:39], v[50:51]
	v_pk_fma_f32 v[28:29], v[34:35], v[36:37], v[48:49]
	v_pk_fma_f32 v[34:35], v[66:67], v[62:63], v[32:33]
	v_pk_fma_f32 v[32:33], v[64:65], v[60:61], v[40:41]
	global_store_dwordx4 v[174:175], v[28:31], off offset:512
	global_store_dwordx4 v[174:175], v[32:35], off offset:528
	s_mov_b64 s[4:5], 0x120200
	v_lshl_add_u64 v[108:109], v[172:173], 0, s[4:5]
	global_load_dwordx4 v[28:31], v[140:141], off offset:512
	global_load_dwordx4 v[32:35], v[108:109], off offset:16
	global_load_dwordx2 v[60:61], v[170:171], off offset:1152
	s_mov_b64 s[4:5], 0x140200
	v_lshl_add_u64 v[110:111], v[172:173], 0, s[4:5]
	s_mov_b64 s[4:5], 0x160200
	s_waitcnt vmcnt(12)
	v_cndmask_b32_e64 v37, v116, 0, s[28:29]
	v_cndmask_b32_e64 v36, v117, 1.0, s[28:29]
	v_pk_mul_f32 v[40:41], v[84:85], v[36:37] op_sel_hi:[1,0]
	v_pk_mul_f32 v[38:39], v[86:87], v[36:37] op_sel_hi:[1,0]
	s_waitcnt vmcnt(11)
	v_sub_f32_e32 v49, v53, v37
	v_sub_f32_e32 v48, v52, v37
	v_sub_f32_e32 v51, v55, v37
	v_sub_f32_e32 v50, v54, v37
	v_pk_mul_f32 v[52:53], v[80:81], v[36:37] op_sel_hi:[1,0]
	v_pk_mul_f32 v[54:55], v[82:83], v[36:37] op_sel_hi:[1,0]
	s_waitcnt vmcnt(10)
	v_sub_f32_e32 v63, v95, v37
	v_sub_f32_e32 v62, v94, v37
	v_sub_f32_e32 v65, v97, v37
	v_sub_f32_e32 v64, v96, v37
	v_pk_fma_f32 v[38:39], v[38:39], v[50:51], v[46:47]
	v_pk_fma_f32 v[36:37], v[40:41], v[48:49], v[44:45]
	v_pk_fma_f32 v[42:43], v[54:55], v[64:65], v[42:43]
	v_pk_fma_f32 v[40:41], v[52:53], v[62:63], v[118:119]
	s_waitcnt vmcnt(7)
	v_cndmask_b32_e64 v45, v102, 0, s[28:29]
	v_cndmask_b32_e64 v44, v103, 1.0, s[28:29]
	global_store_dwordx4 v[156:157], v[36:39], off offset:512
	global_store_dwordx4 v[156:157], v[40:43], off offset:528
	s_waitcnt vmcnt(8)
	v_sub_f32_e32 v49, v57, v45
	v_sub_f32_e32 v48, v56, v45
	v_pk_mul_f32 v[40:41], v[84:85], v[44:45] op_sel_hi:[1,0]
	v_pk_mul_f32 v[42:43], v[86:87], v[44:45] op_sel_hi:[1,0]
	v_sub_f32_e32 v47, v59, v45
	v_sub_f32_e32 v46, v58, v45
	global_load_dwordx2 v[52:53], v[170:171], off offset:1280
	v_pk_mul_f32 v[54:55], v[80:81], v[44:45] op_sel_hi:[1,0]
	v_pk_mul_f32 v[50:51], v[82:83], v[44:45] op_sel_hi:[1,0]
	s_waitcnt vmcnt(8)
	v_sub_f32_e32 v57, v99, v45
	v_sub_f32_e32 v56, v98, v45
	v_sub_f32_e32 v59, v101, v45
	v_sub_f32_e32 v58, v100, v45
	v_pk_fma_f32 v[42:43], v[42:43], v[46:47], v[112:113]
	v_pk_fma_f32 v[40:41], v[40:41], v[48:49], v[114:115]
	global_load_dwordx4 v[36:39], v[104:105], off offset:512
	global_load_dwordx4 v[44:47], v[110:111], off offset:16
	v_pk_fma_f32 v[50:51], v[50:51], v[58:59], v[120:121]
	v_pk_fma_f32 v[48:49], v[54:55], v[56:57], v[122:123]
	global_store_dwordx4 v[148:149], v[40:43], off offset:512
	global_store_dwordx4 v[148:149], v[48:51], off offset:528
	global_load_dwordx2 v[54:55], v[170:171], off offset:1408
	global_load_dwordx4 v[40:43], v[106:107], off offset:512
	v_lshl_add_u64 v[48:49], v[172:173], 0, s[4:5]
	global_load_dwordx4 v[48:51], v[48:49], off offset:16
	v_pk_fma_f32 v[64:65], v[4:5], v[72:73], v[76:77]
	v_pk_fma_f32 v[56:57], v[10:11], v[74:75], v[78:79]
	v_pk_fma_f32 v[58:59], v[8:9], v[72:73], v[76:77]
	s_waitcnt vmcnt(10)
	v_cndmask_b32_e64 v5, v60, 0, s[28:29]
	v_cndmask_b32_e64 v4, v61, 1.0, s[28:29]
	v_pk_fma_f32 v[62:63], v[6:7], v[74:75], v[78:79]
	v_pk_mul_f32 v[8:9], v[84:85], v[4:5] op_sel_hi:[1,0]
	v_pk_mul_f32 v[6:7], v[86:87], v[4:5] op_sel_hi:[1,0]
	v_sub_f32_e32 v11, v29, v5
	v_sub_f32_e32 v10, v28, v5
	v_sub_f32_e32 v29, v31, v5
	v_sub_f32_e32 v28, v30, v5
	v_pk_mul_f32 v[30:31], v[80:81], v[4:5] op_sel_hi:[1,0]
	v_pk_mul_f32 v[60:61], v[82:83], v[4:5] op_sel_hi:[1,0]
	v_sub_f32_e32 v33, v33, v5
	v_sub_f32_e32 v32, v32, v5
	v_sub_f32_e32 v35, v35, v5
	v_sub_f32_e32 v34, v34, v5
	v_pk_fma_f32 v[6:7], v[6:7], v[28:29], v[26:27]
	v_pk_fma_f32 v[4:5], v[8:9], v[10:11], v[24:25]
	v_pk_fma_f32 v[10:11], v[60:61], v[34:35], v[14:15]
	v_pk_fma_f32 v[8:9], v[30:31], v[32:33], v[12:13]
	global_store_dwordx4 v[140:141], v[4:7], off offset:512
	global_store_dwordx4 v[140:141], v[8:11], off offset:528
	s_waitcnt vmcnt(9)
	v_cndmask_b32_e64 v5, v52, 0, s[28:29]
	v_cndmask_b32_e64 v4, v53, 1.0, s[28:29]
	v_pk_mul_f32 v[8:9], v[84:85], v[4:5] op_sel_hi:[1,0]
	v_pk_mul_f32 v[6:7], v[86:87], v[4:5] op_sel_hi:[1,0]
	v_pk_mul_f32 v[14:15], v[80:81], v[4:5] op_sel_hi:[1,0]
	v_pk_mul_f32 v[24:25], v[82:83], v[4:5] op_sel_hi:[1,0]
	s_waitcnt vmcnt(8)
	v_sub_f32_e32 v11, v37, v5
	v_sub_f32_e32 v10, v36, v5
	v_sub_f32_e32 v13, v39, v5
	v_sub_f32_e32 v12, v38, v5
	s_waitcnt vmcnt(7)
	v_sub_f32_e32 v27, v45, v5
	v_sub_f32_e32 v26, v44, v5
	v_sub_f32_e32 v29, v47, v5
	v_sub_f32_e32 v28, v46, v5
	v_pk_fma_f32 v[6:7], v[6:7], v[12:13], v[22:23]
	v_pk_fma_f32 v[4:5], v[8:9], v[10:11], v[20:21]
	v_pk_fma_f32 v[10:11], v[24:25], v[28:29], v[56:57]
	v_pk_fma_f32 v[8:9], v[14:15], v[26:27], v[58:59]
	s_waitcnt vmcnt(4)
	v_cndmask_b32_e64 v22, v54, 0, s[28:29]
	v_cndmask_b32_e64 v12, v55, 1.0, s[28:29]
	global_store_dwordx4 v[104:105], v[4:7], off offset:512
	global_store_dwordx4 v[104:105], v[8:11], off offset:528
	v_pk_mul_f32 v[14:15], v[80:81], v[12:13] op_sel_hi:[1,0]
	v_pk_mul_f32 v[4:5], v[84:85], v[12:13] op_sel_hi:[1,0]
	v_pk_mul_f32 v[6:7], v[86:87], v[12:13] op_sel_hi:[1,0]
	s_waitcnt vmcnt(5)
	v_sub_f32_e32 v9, v41, v22
	v_sub_f32_e32 v8, v40, v22
	v_sub_f32_e32 v11, v43, v22
	v_sub_f32_e32 v10, v42, v22
	v_pk_mul_f32 v[12:13], v[82:83], v[12:13] op_sel_hi:[1,0]
	s_waitcnt vmcnt(4)
	v_sub_f32_e32 v21, v49, v22
	v_sub_f32_e32 v20, v48, v22
	v_sub_f32_e32 v23, v51, v22
	v_sub_f32_e32 v22, v50, v22
	v_pk_fma_f32 v[6:7], v[6:7], v[10:11], v[18:19]
	v_pk_fma_f32 v[4:5], v[4:5], v[8:9], v[16:17]
	v_pk_fma_f32 v[10:11], v[12:13], v[22:23], v[62:63]
	v_pk_fma_f32 v[8:9], v[14:15], v[20:21], v[64:65]
	global_store_dwordx4 v[106:107], v[4:7], off offset:512
	global_store_dwordx4 v[106:107], v[8:11], off offset:528
	s_cbranch_vccnz .LBB0_1057
	s_andn2_b64 vcc, exec, s[18:19]
	s_cbranch_vccnz .LBB0_1056
	s_barrier
	s_branch .LBB0_1056

; #define RES_LOADG(slot, g_) do { const int ro_ = ((g_) >> 2) * HALF + ((g_) & 3) * 16; \
;                 _Pragma("unroll") for (int n = 0; n < 2; ++n) xa[slot][n] = *(const f32x4*)(sl + rbase + (size_t)ro_ * 2048 + bj * HALF + 4 * n); \
;                 ms[slot] = *(const f2_t_*)(stp + 2 * (row0 + ro_)); } while (0)
;     __device__ __forceinline__ void operator()(const f32x4 (&acc)[2][2][4][2], const Unit& u, int wr, int wc, int fr, int fq) const {
;     ...
;         for (int bj = 0; bj < 2; ++bj) {
;             f32x4 mv[2], ag[2], ab[2];
; #pragma unroll
;             for (int n = 0; n < 2; ++n) { mv[n] = *(const f32x4*)(mp + col0 + bj * HALF + 4 * n) * coef;
;                 const f32x4 g4 = *(const f32x4*)(lg + col0 + bj * HALF + 4 * n), b4 = *(const f32x4*)(lb + col0 + bj * HALF + 4 * n);
;                 const f32x4 g4s = ln ? g4 : (f32x4){1.f, 1.f, 1.f, 1.f}, b4s = ln ? b4 : (f32x4){0.f, 0.f, 0.f, 0.f};
;                 ag[n] = g4s * al; ab[n] = b4s * al; }
;             f32x4 xa[3][2]; f2_t_ ms[3];
;     ...
;             RES_LOADG(0, 0); RES_LOADG(1, 1);
; #pragma unroll
;             for (int gi = 0; gi < 8; ++gi) {
;                 const int ai = gi >> 2, m = gi & 3;
;                 if (gi + 2 < 8) RES_LOADG((gi + 2) % 3, gi + 2);
;                 asm volatile("" ::: "memory");
;                 float* rowp = xl + rbase + (size_t)(ai * HALF + m * 16) * 2048 + bj * HALF;
;                 const float mean = ln ? ms[gi % 3][0] : 0.f, rstd = ln ? ms[gi % 3][1] : 1.f;
; #pragma unroll
;                 for (int n = 0; n < 2; ++n) { const f32x4 t = ag[n] * rstd;
;                     *(f32x4*)(rowp + 4 * n) = (xa[gi % 3][n] - mean) * t + (ab[n] + mv[n] * acc[ai][bj][m][n]); }
;                 asm volatile("" ::: "memory");
;             }
.LBB0_1337:
.LBB0_1339:
	s_waitcnt vmcnt(0)
	v_pk_mul_f32 v[140:141], v[140:141], s[40:41] op_sel_hi:[1,0]
	v_pk_mul_f32 v[208:209], v[132:133], 0.5 op_sel_hi:[1,0]
	v_cndmask_b32_e64 v188, v140, 0, s[28:29]
	v_lshl_add_u32 v140, s71, 8, v216
	v_cndmask_b32_e64 v189, v141, 0, s[28:29]
	v_ashrrev_i32_e32 v141, 31, v140
	v_pk_mul_f32 v[132:133], v[138:139], s[40:41] op_sel_hi:[1,0]
	s_mov_b64 s[38:39], 0x20000
	v_cndmask_b32_e64 v207, v133, 0, s[28:29]
	v_cndmask_b32_e64 v206, v132, 0, s[28:29]
	v_lshlrev_b64 v[132:133], 13, v[140:141]
	v_lshl_add_u64 v[132:133], s[8:9], 0, v[132:133]
	v_lshl_add_u64 v[164:165], v[148:149], 2, v[132:133]
	v_pk_mul_f32 v[142:143], v[142:143], s[40:41] op_sel_hi:[1,0]
	v_lshl_add_u64 v[132:133], v[164:165], 0, s[38:39]
	s_mov_b32 s38, 0x20000
	v_cndmask_b32_e64 v190, v142, 0, s[28:29]
	v_lshlrev_b32_e32 v142, 1, v140
	v_add_co_u32_e32 v168, vcc, s38, v164
	v_cndmask_b32_e64 v191, v143, 0, s[28:29]
	v_ashrrev_i32_e32 v143, 31, v142
	v_addc_co_u32_e32 v169, vcc, 0, v165, vcc
	v_pk_mul_f32 v[186:187], v[146:147], 0.5 op_sel_hi:[1,0]
	v_pk_mul_f32 v[184:185], v[144:145], 0.5 op_sel_hi:[1,0]
	v_lshl_add_u64 v[162:163], v[142:143], 2, s[30:31]
	global_load_dwordx4 v[148:151], v[164:165], off offset:16
	global_load_dwordx4 v[220:223], v[164:165], off
	global_load_dwordx4 v[144:147], v[168:169], off
	global_load_dwordx4 v[140:143], v[132:133], off offset:16
	global_load_dwordx2 v[192:193], v[162:163], off
	global_load_dwordx2 v[214:215], v[162:163], off offset:128
	s_mov_b64 s[38:39], 0x40000
	v_pk_mul_f32 v[210:211], v[134:135], 0.5 op_sel_hi:[1,0]
	v_lshl_add_u64 v[132:133], v[164:165], 0, s[38:39]
	s_mov_b32 s38, 0x40000
	v_pk_mul_f32 v[134:135], v[136:137], s[40:41] op_sel_hi:[1,0]
	v_add_co_u32_e32 v166, vcc, s38, v164
	v_pk_fma_f32 v[130:131], v[130:131], v[210:211], v[190:191]
	v_pk_fma_f32 v[128:129], v[128:129], v[208:209], v[188:189]
	v_cndmask_b32_e64 v205, v135, 0, s[28:29]
	v_cndmask_b32_e64 v204, v134, 0, s[28:29]
	v_addc_co_u32_e32 v167, vcc, 0, v165, vcc
	global_load_dwordx4 v[136:139], v[166:167], off
	s_nop 0
	global_load_dwordx4 v[132:135], v[132:133], off offset:16
	s_nop 0
	global_load_dwordx2 v[212:213], v[162:163], off offset:256
	v_pk_fma_f32 v[126:127], v[126:127], v[186:187], v[206:207]
	v_pk_fma_f32 v[124:125], v[124:125], v[184:185], v[204:205]
	s_mov_b64 s[38:39], 0x60000
	v_pk_fma_f32 v[122:123], v[122:123], v[210:211], v[190:191]
	v_pk_fma_f32 v[120:121], v[120:121], v[208:209], v[188:189]
	v_pk_fma_f32 v[118:119], v[118:119], v[186:187], v[206:207]
	v_pk_fma_f32 v[116:117], v[116:117], v[184:185], v[204:205]
	v_pk_fma_f32 v[114:115], v[114:115], v[210:211], v[190:191]
	v_pk_fma_f32 v[112:113], v[112:113], v[208:209], v[188:189]
	v_pk_fma_f32 v[110:111], v[110:111], v[186:187], v[206:207]
	v_pk_fma_f32 v[108:109], v[108:109], v[184:185], v[204:205]
	v_pk_fma_f32 v[106:107], v[106:107], v[210:211], v[190:191]
	v_pk_fma_f32 v[104:105], v[104:105], v[208:209], v[188:189]
	v_pk_fma_f32 v[102:103], v[102:103], v[186:187], v[206:207]
	v_pk_fma_f32 v[100:101], v[100:101], v[184:185], v[204:205]
	v_pk_fma_f32 v[98:99], v[98:99], v[210:211], v[190:191]
	v_pk_fma_f32 v[96:97], v[96:97], v[208:209], v[188:189]
	v_pk_fma_f32 v[94:95], v[94:95], v[186:187], v[206:207]
	v_pk_fma_f32 v[92:93], v[92:93], v[184:185], v[204:205]
	v_pk_fma_f32 v[90:91], v[90:91], v[210:211], v[190:191]
	v_pk_fma_f32 v[88:89], v[88:89], v[208:209], v[188:189]
	v_pk_fma_f32 v[86:87], v[86:87], v[186:187], v[206:207]
	v_pk_fma_f32 v[84:85], v[84:85], v[184:185], v[204:205]
	v_pk_fma_f32 v[82:83], v[82:83], v[210:211], v[190:191]
	v_pk_fma_f32 v[80:81], v[80:81], v[208:209], v[188:189]
	v_pk_fma_f32 v[78:79], v[78:79], v[186:187], v[206:207]
	v_pk_fma_f32 v[76:77], v[76:77], v[184:185], v[204:205]
	v_pk_fma_f32 v[74:75], v[74:75], v[210:211], v[190:191]
	v_pk_fma_f32 v[72:73], v[72:73], v[208:209], v[188:189]
	v_pk_fma_f32 v[70:71], v[70:71], v[186:187], v[206:207]
	v_pk_fma_f32 v[68:69], v[68:69], v[184:185], v[204:205]
	s_waitcnt vmcnt(4)
	v_cndmask_b32_e64 v228, v192, 0, s[28:29]
	v_cndmask_b32_e64 v192, v193, 1.0, s[28:29]
	v_pk_mul_f32 v[196:197], v[180:181], v[192:193] op_sel_hi:[1,0]
	v_pk_mul_f32 v[198:199], v[178:179], v[192:193] op_sel_hi:[1,0]
	v_sub_f32_e32 v201, v221, v228
	v_sub_f32_e32 v200, v220, v228
	v_sub_f32_e32 v203, v223, v228
	v_sub_f32_e32 v202, v222, v228
	v_pk_fma_f32 v[130:131], v[198:199], v[202:203], v[130:131]
	v_pk_fma_f32 v[128:129], v[196:197], v[200:201], v[128:129]
	global_store_dwordx4 v[164:165], v[128:131], off
	v_sub_f32_e32 v149, v149, v228
	v_sub_f32_e32 v148, v148, v228
	v_pk_mul_f32 v[128:129], v[176:177], v[192:193] op_sel_hi:[1,0]
	v_pk_mul_f32 v[130:131], v[182:183], v[192:193] op_sel_hi:[1,0]
	v_sub_f32_e32 v151, v151, v228
	v_sub_f32_e32 v150, v150, v228
	v_pk_fma_f32 v[126:127], v[130:131], v[150:151], v[126:127]
	v_pk_fma_f32 v[124:125], v[128:129], v[148:149], v[124:125]
	global_store_dwordx4 v[164:165], v[124:127], off offset:16
	s_waitcnt vmcnt(5)
; #define RES_LOADG(slot, g_) do { const int ro_ = ((g_) >> 2) * HALF + ((g_) & 3) * 16; \
;                 _Pragma("unroll") for (int n = 0; n < 2; ++n) xa[slot][n] = *(const f32x4*)(sl + rbase + (size_t)ro_ * 2048 + bj * HALF + 4 * n); \
;                 ms[slot] = *(const f2_t_*)(stp + 2 * (row0 + ro_)); } while (0)
;     __device__ __forceinline__ void operator()(const f32x4 (&acc)[2][2][4][2], const Unit& u, int wr, int wc, int fr, int fq) const {
;     ...
;             for (int gi = 0; gi < 8; ++gi) {
;                 const int ai = gi >> 2, m = gi & 3;
;                 if (gi + 2 < 8) RES_LOADG((gi + 2) % 3, gi + 2);
;                 asm volatile("" ::: "memory");
;                 float* rowp = xl + rbase + (size_t)(ai * HALF + m * 16) * 2048 + bj * HALF;
;                 const float mean = ln ? ms[gi % 3][0] : 0.f, rstd = ln ? ms[gi % 3][1] : 1.f;
; #pragma unroll
;                 for (int n = 0; n < 2; ++n) { const f32x4 t = ag[n] * rstd;
;                     *(f32x4*)(rowp + 4 * n) = (xa[gi % 3][n] - mean) * t + (ab[n] + mv[n] * acc[ai][bj][m][n]); }
;                 asm volatile("" ::: "memory");
;             }
	v_cndmask_b32_e64 v193, v214, 0, s[28:29]
	v_cndmask_b32_e64 v192, v215, 1.0, s[28:29]
	v_lshl_add_u64 v[124:125], v[164:165], 0, s[38:39]
	s_mov_b32 s38, 0x60000
	v_add_co_u32_e32 v148, vcc, s38, v164
	v_pk_mul_f32 v[196:197], v[180:181], v[192:193] op_sel_hi:[1,0]
	v_pk_mul_f32 v[198:199], v[178:179], v[192:193] op_sel_hi:[1,0]
	v_sub_f32_e32 v145, v145, v193
	v_sub_f32_e32 v144, v144, v193
	v_sub_f32_e32 v147, v147, v193
	v_sub_f32_e32 v146, v146, v193
	v_addc_co_u32_e32 v149, vcc, 0, v165, vcc
	v_pk_fma_f32 v[122:123], v[198:199], v[146:147], v[122:123]
	v_pk_fma_f32 v[120:121], v[196:197], v[144:145], v[120:121]
	global_load_dwordx4 v[128:131], v[148:149], off
	s_nop 0
	global_load_dwordx4 v[124:127], v[124:125], off offset:16
	s_nop 0
	global_load_dwordx2 v[150:151], v[162:163], off offset:384
	global_store_dwordx4 v[168:169], v[120:123], off
	v_pk_mul_f32 v[144:145], v[182:183], v[192:193] op_sel_hi:[1,0]
	s_mov_b64 s[38:39], 0x100000
	v_pk_mul_f32 v[120:121], v[176:177], v[192:193] op_sel_hi:[1,0]
	v_sub_f32_e32 v123, v141, v193
	v_sub_f32_e32 v122, v140, v193
	v_sub_f32_e32 v141, v143, v193
	v_sub_f32_e32 v140, v142, v193
	v_pk_fma_f32 v[118:119], v[144:145], v[140:141], v[118:119]
	v_pk_fma_f32 v[116:117], v[120:121], v[122:123], v[116:117]
	global_store_dwordx4 v[168:169], v[116:119], off offset:16
	s_waitcnt vmcnt(7)
	v_cndmask_b32_e64 v145, v212, 0, s[28:29]
	v_cndmask_b32_e64 v144, v213, 1.0, s[28:29]
	v_lshl_add_u64 v[116:117], v[164:165], 0, s[38:39]
	s_mov_b32 s38, 0x100000
	v_add_co_u32_e32 v140, vcc, s38, v164
	v_pk_mul_f32 v[146:147], v[180:181], v[144:145] op_sel_hi:[1,0]
	s_nop 0
	v_addc_co_u32_e32 v141, vcc, 0, v165, vcc
	global_load_dwordx4 v[120:123], v[140:141], off
	s_nop 0
	global_load_dwordx4 v[116:119], v[116:117], off offset:16
	s_nop 0
	global_load_dwordx2 v[142:143], v[162:163], off offset:1024
	v_pk_mul_f32 v[192:193], v[178:179], v[144:145] op_sel_hi:[1,0]
	v_sub_f32_e32 v137, v137, v145
	v_sub_f32_e32 v136, v136, v145
	v_sub_f32_e32 v139, v139, v145
	v_sub_f32_e32 v138, v138, v145
	v_pk_fma_f32 v[114:115], v[192:193], v[138:139], v[114:115]
	v_pk_fma_f32 v[112:113], v[146:147], v[136:137], v[112:113]
	global_store_dwordx4 v[166:167], v[112:115], off
	v_sub_f32_e32 v133, v133, v145
	v_sub_f32_e32 v132, v132, v145
	v_pk_mul_f32 v[112:113], v[176:177], v[144:145] op_sel_hi:[1,0]
	v_pk_mul_f32 v[114:115], v[182:183], v[144:145] op_sel_hi:[1,0]
	v_sub_f32_e32 v135, v135, v145
	v_sub_f32_e32 v134, v134, v145
	v_pk_fma_f32 v[110:111], v[114:115], v[134:135], v[110:111]
	v_pk_fma_f32 v[108:109], v[112:113], v[132:133], v[108:109]
	s_mov_b64 s[38:39], 0x120000
	global_store_dwordx4 v[166:167], v[108:111], off offset:16
	s_waitcnt vmcnt(7)
	v_cndmask_b32_e64 v137, v150, 0, s[28:29]
	v_lshl_add_u64 v[108:109], v[164:165], 0, s[38:39]
	s_mov_b32 s38, 0x120000
	v_cndmask_b32_e64 v136, v151, 1.0, s[28:29]
	v_add_co_u32_e32 v132, vcc, s38, v164
	v_pk_mul_f32 v[138:139], v[180:181], v[136:137] op_sel_hi:[1,0]
	v_pk_mul_f32 v[144:145], v[178:179], v[136:137] op_sel_hi:[1,0]
	v_sub_f32_e32 v129, v129, v137
	v_sub_f32_e32 v128, v128, v137
	v_sub_f32_e32 v131, v131, v137
	v_sub_f32_e32 v130, v130, v137
	v_addc_co_u32_e32 v133, vcc, 0, v165, vcc
	v_pk_fma_f32 v[106:107], v[144:145], v[130:131], v[106:107]
	v_pk_fma_f32 v[104:105], v[138:139], v[128:129], v[104:105]
	global_load_dwordx4 v[112:115], v[132:133], off
	s_nop 0
	global_load_dwordx4 v[108:111], v[108:109], off offset:16
	s_nop 0
	global_load_dwordx2 v[134:135], v[162:163], off offset:1152
	global_store_dwordx4 v[148:149], v[104:107], off
	v_sub_f32_e32 v125, v125, v137
	v_sub_f32_e32 v124, v124, v137
	v_pk_mul_f32 v[104:105], v[176:177], v[136:137] op_sel_hi:[1,0]
	v_pk_mul_f32 v[106:107], v[182:183], v[136:137] op_sel_hi:[1,0]
	v_sub_f32_e32 v127, v127, v137
	v_sub_f32_e32 v126, v126, v137
	v_pk_fma_f32 v[102:103], v[106:107], v[126:127], v[102:103]
	v_pk_fma_f32 v[100:101], v[104:105], v[124:125], v[100:101]
	s_mov_b64 s[38:39], 0x140000
	global_store_dwordx4 v[148:149], v[100:103], off offset:16
	s_waitcnt vmcnt(7)
; #define RES_LOADG(slot, g_) do { const int ro_ = ((g_) >> 2) * HALF + ((g_) & 3) * 16; \
;                 _Pragma("unroll") for (int n = 0; n < 2; ++n) xa[slot][n] = *(const f32x4*)(sl + rbase + (size_t)ro_ * 2048 + bj * HALF + 4 * n); \
;                 ms[slot] = *(const f2_t_*)(stp + 2 * (row0 + ro_)); } while (0)
;     __device__ __forceinline__ void operator()(const f32x4 (&acc)[2][2][4][2], const Unit& u, int wr, int wc, int fr, int fq) const {
;     ...
;             for (int n = 0; n < 2; ++n) { mv[n] = *(const f32x4*)(mp + col0 + bj * HALF + 4 * n) * coef;
;                 const f32x4 g4 = *(const f32x4*)(lg + col0 + bj * HALF + 4 * n), b4 = *(const f32x4*)(lb + col0 + bj * HALF + 4 * n);
;                 const f32x4 g4s = ln ? g4 : (f32x4){1.f, 1.f, 1.f, 1.f}, b4s = ln ? b4 : (f32x4){0.f, 0.f, 0.f, 0.f};
;                 ag[n] = g4s * al; ab[n] = b4s * al; }
;     ...
;             for (int gi = 0; gi < 8; ++gi) {
;                 const int ai = gi >> 2, m = gi & 3;
;                 if (gi + 2 < 8) RES_LOADG((gi + 2) % 3, gi + 2);
;                 asm volatile("" ::: "memory");
;                 float* rowp = xl + rbase + (size_t)(ai * HALF + m * 16) * 2048 + bj * HALF;
;                 const float mean = ln ? ms[gi % 3][0] : 0.f, rstd = ln ? ms[gi % 3][1] : 1.f;
; #pragma unroll
;                 for (int n = 0; n < 2; ++n) { const f32x4 t = ag[n] * rstd;
;                     *(f32x4*)(rowp + 4 * n) = (xa[gi % 3][n] - mean) * t + (ab[n] + mv[n] * acc[ai][bj][m][n]); }
;                 asm volatile("" ::: "memory");
;             }
	v_cndmask_b32_e64 v138, v142, 0, s[28:29]
	v_cndmask_b32_e64 v106, v143, 1.0, s[28:29]
	v_lshl_add_u64 v[100:101], v[164:165], 0, s[38:39]
	s_mov_b32 s38, 0x140000
	v_add_co_u32_e32 v104, vcc, s38, v164
	v_pk_mul_f32 v[130:131], v[180:181], v[106:107] op_sel_hi:[1,0]
	v_pk_mul_f32 v[136:137], v[178:179], v[106:107] op_sel_hi:[1,0]
	v_sub_f32_e32 v121, v121, v138
	v_sub_f32_e32 v120, v120, v138
	v_sub_f32_e32 v123, v123, v138
	v_sub_f32_e32 v122, v122, v138
	v_addc_co_u32_e32 v105, vcc, 0, v165, vcc
	v_pk_fma_f32 v[98:99], v[136:137], v[122:123], v[98:99]
	v_pk_fma_f32 v[96:97], v[130:131], v[120:121], v[96:97]
	global_load_dwordx4 v[124:127], v[104:105], off
	s_nop 0
	global_load_dwordx4 v[100:103], v[100:101], off offset:16
	s_nop 0
	global_load_dwordx2 v[128:129], v[162:163], off offset:1280
	global_store_dwordx4 v[140:141], v[96:99], off
	s_mov_b64 s[38:39], 0x160000
	s_nop 0
	v_pk_mul_f32 v[96:97], v[176:177], v[106:107] op_sel_hi:[1,0]
	v_pk_mul_f32 v[98:99], v[182:183], v[106:107] op_sel_hi:[1,0]
	v_sub_f32_e32 v107, v117, v138
	v_sub_f32_e32 v106, v116, v138
	v_sub_f32_e32 v117, v119, v138
	v_sub_f32_e32 v116, v118, v138
	v_pk_fma_f32 v[94:95], v[98:99], v[116:117], v[94:95]
	v_pk_fma_f32 v[92:93], v[96:97], v[106:107], v[92:93]
	global_store_dwordx4 v[140:141], v[92:95], off offset:16
	s_waitcnt vmcnt(7)
	v_cndmask_b32_e64 v119, v134, 0, s[28:29]
	v_lshl_add_u64 v[92:93], v[164:165], 0, s[38:39]
	s_mov_b32 s38, 0x160000
	v_add_co_u32_e32 v106, vcc, s38, v164
	v_cndmask_b32_e64 v118, v135, 1.0, s[28:29]
	s_nop 0
	v_addc_co_u32_e32 v107, vcc, 0, v165, vcc
	global_load_dwordx4 v[96:99], v[106:107], off
	s_nop 0
	global_load_dwordx4 v[92:95], v[92:93], off offset:16
	s_nop 0
	global_load_dwordx2 v[116:117], v[162:163], off offset:1408
	v_pk_mul_f32 v[120:121], v[180:181], v[118:119] op_sel_hi:[1,0]
	v_pk_mul_f32 v[122:123], v[178:179], v[118:119] op_sel_hi:[1,0]
	v_sub_f32_e32 v113, v113, v119
	v_sub_f32_e32 v112, v112, v119
	v_sub_f32_e32 v115, v115, v119
	v_sub_f32_e32 v114, v114, v119
	v_pk_fma_f32 v[90:91], v[122:123], v[114:115], v[90:91]
	v_pk_fma_f32 v[88:89], v[120:121], v[112:113], v[88:89]
	global_store_dwordx4 v[132:133], v[88:91], off
	v_sub_f32_e32 v109, v109, v119
	v_sub_f32_e32 v108, v108, v119
	v_pk_mul_f32 v[88:89], v[176:177], v[118:119] op_sel_hi:[1,0]
	v_pk_mul_f32 v[90:91], v[182:183], v[118:119] op_sel_hi:[1,0]
	v_sub_f32_e32 v111, v111, v119
	v_sub_f32_e32 v110, v110, v119
	v_pk_fma_f32 v[86:87], v[90:91], v[110:111], v[86:87]
	v_pk_fma_f32 v[84:85], v[88:89], v[108:109], v[84:85]
	global_store_dwordx4 v[132:133], v[84:87], off offset:16
	s_waitcnt vmcnt(7)
	v_cndmask_b32_e64 v110, v128, 0, s[28:29]
	v_sub_f32_e32 v91, v125, v110
	v_cndmask_b32_e64 v84, v129, 1.0, s[28:29]
	v_pk_mul_f32 v[86:87], v[180:181], v[84:85] op_sel_hi:[1,0]
	v_pk_mul_f32 v[88:89], v[178:179], v[84:85] op_sel_hi:[1,0]
	v_sub_f32_e32 v90, v124, v110
	v_sub_f32_e32 v109, v127, v110
	v_sub_f32_e32 v108, v126, v110
	v_pk_fma_f32 v[82:83], v[88:89], v[108:109], v[82:83]
	v_pk_fma_f32 v[80:81], v[86:87], v[90:91], v[80:81]
	global_store_dwordx4 v[104:105], v[80:83], off
	v_sub_f32_e32 v87, v103, v110
	v_sub_f32_e32 v86, v102, v110
	v_pk_mul_f32 v[80:81], v[176:177], v[84:85] op_sel_hi:[1,0]
	v_pk_mul_f32 v[82:83], v[182:183], v[84:85] op_sel_hi:[1,0]
	v_sub_f32_e32 v85, v101, v110
	v_sub_f32_e32 v84, v100, v110
	v_pk_fma_f32 v[78:79], v[82:83], v[86:87], v[78:79]
	v_pk_fma_f32 v[76:77], v[80:81], v[84:85], v[76:77]
	global_store_dwordx4 v[104:105], v[76:79], off offset:16
	s_and_b64 vcc, exec, s[4:5]
	v_mov_b32_e32 v87, 0x3fb504f3
	s_waitcnt vmcnt(4)
	v_cndmask_b32_e64 v86, v116, 0, s[28:29]
	v_cndmask_b32_e64 v76, v117, 1.0, s[28:29]
	v_pk_mul_f32 v[78:79], v[180:181], v[76:77] op_sel_hi:[1,0]
	v_pk_mul_f32 v[80:81], v[178:179], v[76:77] op_sel_hi:[1,0]
	v_sub_f32_e32 v83, v97, v86
	v_sub_f32_e32 v82, v96, v86
	v_sub_f32_e32 v85, v99, v86
	v_sub_f32_e32 v84, v98, v86
	v_pk_fma_f32 v[74:75], v[80:81], v[84:85], v[74:75]
	v_pk_fma_f32 v[72:73], v[78:79], v[82:83], v[72:73]
	global_store_dwordx4 v[106:107], v[72:75], off
	v_sub_f32_e32 v79, v95, v86
	v_sub_f32_e32 v78, v94, v86
	v_pk_mul_f32 v[72:73], v[176:177], v[76:77] op_sel_hi:[1,0]
	v_pk_mul_f32 v[74:75], v[182:183], v[76:77] op_sel_hi:[1,0]
	v_sub_f32_e32 v77, v93, v86
	v_sub_f32_e32 v76, v92, v86
	v_pk_fma_f32 v[70:71], v[74:75], v[78:79], v[70:71]
	v_pk_fma_f32 v[68:69], v[72:73], v[76:77], v[68:69]
	global_store_dwordx4 v[106:107], v[68:71], off offset:16
	global_load_dwordx4 v[68:71], v[174:175], off offset:512
	global_load_dwordx4 v[80:83], v[170:171], off offset:512
	v_mov_b32_e32 v84, 0x3fb504f3
	v_mov_b32_e32 v85, 0x3fb504f3
	v_mov_b32_e32 v86, 0x3fb504f3
	global_load_dwordx4 v[76:79], v[174:175], off offset:528
	global_load_dwordx4 v[72:75], v[170:171], off offset:528
	s_cbranch_vccnz .LBB0_1343
	global_load_dwordx4 v[244:247], v[172:173], off offset:512
	global_load_dwordx4 v[92:95], v[172:173], off offset:528
	s_waitcnt vmcnt(0)
	v_pk_mul_f32 v[86:87], v[246:247], s[40:41] op_sel_hi:[1,0]
	v_pk_mul_f32 v[84:85], v[244:245], s[40:41] op_sel_hi:[1,0]
	v_pk_mul_f32 v[90:91], v[82:83], s[40:41] op_sel_hi:[1,0]
	v_pk_mul_f32 v[88:89], v[80:81], s[40:41] op_sel_hi:[1,0]
	v_pk_mul_f32 v[82:83], v[94:95], s[40:41] op_sel_hi:[1,0]
	v_pk_mul_f32 v[80:81], v[92:93], s[40:41] op_sel_hi:[1,0]
	s_branch .LBB0_1344

; #define RES_LOADG(slot, g_) do { const int ro_ = ((g_) >> 2) * HALF + ((g_) & 3) * 16; \
;                 _Pragma("unroll") for (int n = 0; n < 2; ++n) xa[slot][n] = *(const f32x4*)(sl + rbase + (size_t)ro_ * 2048 + bj * HALF + 4 * n); \
;                 ms[slot] = *(const f2_t_*)(stp + 2 * (row0 + ro_)); } while (0)
;     __device__ __forceinline__ void operator()(const f32x4 (&acc)[2][2][4][2], const Unit& u, int wr, int wc, int fr, int fq) const {
;     ...
;         for (int bj = 0; bj < 2; ++bj) {
;             f32x4 mv[2], ag[2], ab[2];
; #pragma unroll
;             for (int n = 0; n < 2; ++n) { mv[n] = *(const f32x4*)(mp + col0 + bj * HALF + 4 * n) * coef;
;                 const f32x4 g4 = *(const f32x4*)(lg + col0 + bj * HALF + 4 * n), b4 = *(const f32x4*)(lb + col0 + bj * HALF + 4 * n);
;                 const f32x4 g4s = ln ? g4 : (f32x4){1.f, 1.f, 1.f, 1.f}, b4s = ln ? b4 : (f32x4){0.f, 0.f, 0.f, 0.f};
;                 ag[n] = g4s * al; ab[n] = b4s * al; }
;             f32x4 xa[3][2]; f2_t_ ms[3];
;     ...
;             RES_LOADG(0, 0); RES_LOADG(1, 1);
; #pragma unroll
;             for (int gi = 0; gi < 8; ++gi) {
;                 const int ai = gi >> 2, m = gi & 3;
;                 if (gi + 2 < 8) RES_LOADG((gi + 2) % 3, gi + 2);
;                 asm volatile("" ::: "memory");
;                 float* rowp = xl + rbase + (size_t)(ai * HALF + m * 16) * 2048 + bj * HALF;
;                 const float mean = ln ? ms[gi % 3][0] : 0.f, rstd = ln ? ms[gi % 3][1] : 1.f;
; #pragma unroll
;                 for (int n = 0; n < 2; ++n) { const f32x4 t = ag[n] * rstd;
;                     *(f32x4*)(rowp + 4 * n) = (xa[gi % 3][n] - mean) * t + (ab[n] + mv[n] * acc[ai][bj][m][n]); }
;                 asm volatile("" ::: "memory");
;             }
.LBB0_1344:
	global_load_dwordx2 v[102:103], v[162:163], off
	global_load_dwordx2 v[124:125], v[162:163], off offset:128
	global_load_dwordx4 v[108:111], v[164:165], off offset:512
	global_load_dwordx4 v[112:115], v[164:165], off offset:528
	global_load_dwordx4 v[116:119], v[168:169], off offset:512
	s_mov_b64 s[4:5], 0x20200
	v_lshl_add_u64 v[92:93], v[164:165], 0, s[4:5]
	global_load_dwordx4 v[120:123], v[92:93], off offset:16
	v_pk_mul_f32 v[94:95], v[70:71], 0.5 op_sel_hi:[1,0]
	v_pk_mul_f32 v[70:71], v[72:73], s[40:41] op_sel_hi:[1,0]
	v_pk_mul_f32 v[76:77], v[76:77], 0.5 op_sel_hi:[1,0]
	v_pk_mul_f32 v[92:93], v[68:69], 0.5 op_sel_hi:[1,0]
	v_pk_mul_f32 v[68:69], v[74:75], s[40:41] op_sel_hi:[1,0]
	v_cndmask_b32_e64 v97, v71, 0, s[28:29]
	v_cndmask_b32_e64 v96, v70, 0, s[28:29]
	v_pk_mul_f32 v[78:79], v[78:79], 0.5 op_sel_hi:[1,0]
	s_mov_b64 s[4:5], 0x40200
	v_cndmask_b32_e64 v99, v69, 0, s[28:29]
	v_cndmask_b32_e64 v98, v68, 0, s[28:29]
	v_pk_fma_f32 v[134:135], v[52:53], v[76:77], v[96:97]
	v_lshl_add_u64 v[126:127], v[164:165], 0, s[4:5]
	v_pk_fma_f32 v[66:67], v[66:67], v[94:95], v[90:91]
	v_pk_fma_f32 v[64:65], v[64:65], v[92:93], v[88:89]
	v_pk_fma_f32 v[130:131], v[54:55], v[78:79], v[98:99]
	global_load_dwordx2 v[100:101], v[162:163], off offset:256
	global_load_dwordx4 v[72:75], v[166:167], off offset:512
	global_load_dwordx4 v[68:71], v[126:127], off offset:16
	v_pk_fma_f32 v[126:127], v[60:61], v[92:93], v[88:89]
	v_pk_fma_f32 v[58:59], v[58:59], v[78:79], v[98:99]
	v_pk_fma_f32 v[56:57], v[56:57], v[76:77], v[96:97]
	s_mov_b64 s[4:5], 0x60200
	v_pk_fma_f32 v[62:63], v[62:63], v[94:95], v[90:91]
	v_lshl_add_u64 v[128:129], v[164:165], 0, s[4:5]
	s_mov_b64 s[4:5], 0x100200
	v_pk_fma_f32 v[50:51], v[50:51], v[94:95], v[90:91]
	v_pk_fma_f32 v[48:49], v[48:49], v[92:93], v[88:89]
	v_pk_fma_f32 v[40:41], v[40:41], v[76:77], v[96:97]
	v_pk_fma_f32 v[46:47], v[46:47], v[94:95], v[90:91]
	v_pk_fma_f32 v[44:45], v[44:45], v[92:93], v[88:89]
	v_pk_fma_f32 v[26:27], v[26:27], v[94:95], v[90:91]
	v_pk_fma_f32 v[24:25], v[24:25], v[92:93], v[88:89]
	v_pk_fma_f32 v[14:15], v[14:15], v[78:79], v[98:99]
	v_pk_fma_f32 v[12:13], v[12:13], v[76:77], v[96:97]
	v_pk_fma_f32 v[22:23], v[22:23], v[94:95], v[90:91]
	v_pk_fma_f32 v[20:21], v[20:21], v[92:93], v[88:89]
	v_pk_fma_f32 v[18:19], v[18:19], v[94:95], v[90:91]
	v_pk_fma_f32 v[16:17], v[16:17], v[92:93], v[88:89]
	s_and_b64 vcc, exec, s[2:3]
	s_mov_b64 s[2:3], -1
	s_waitcnt vmcnt(8)
	v_cndmask_b32_e64 v53, v102, 0, s[28:29]
	v_cndmask_b32_e64 v52, v103, 1.0, s[28:29]
	v_pk_mul_f32 v[102:103], v[84:85], v[52:53] op_sel_hi:[1,0]
	v_pk_mul_f32 v[54:55], v[86:87], v[52:53] op_sel_hi:[1,0]
	s_waitcnt vmcnt(6)
	v_sub_f32_e32 v109, v109, v53
	v_sub_f32_e32 v108, v108, v53
	v_sub_f32_e32 v111, v111, v53
	v_sub_f32_e32 v110, v110, v53
	v_cndmask_b32_e64 v61, v124, 0, s[28:29]
	v_cndmask_b32_e64 v60, v125, 1.0, s[28:29]
	v_pk_mul_f32 v[124:125], v[80:81], v[52:53] op_sel_hi:[1,0]
	v_pk_mul_f32 v[136:137], v[82:83], v[52:53] op_sel_hi:[1,0]
	s_waitcnt vmcnt(5)
	v_sub_f32_e32 v113, v113, v53
	v_sub_f32_e32 v112, v112, v53
	v_sub_f32_e32 v115, v115, v53
	v_sub_f32_e32 v114, v114, v53
	v_pk_fma_f32 v[54:55], v[54:55], v[110:111], v[66:67]
	v_pk_fma_f32 v[52:53], v[102:103], v[108:109], v[64:65]
	v_pk_fma_f32 v[58:59], v[136:137], v[114:115], v[58:59]
	v_pk_fma_f32 v[56:57], v[124:125], v[112:113], v[56:57]
	global_store_dwordx4 v[164:165], v[52:55], off offset:512
	global_store_dwordx4 v[164:165], v[56:59], off offset:528
	v_pk_mul_f32 v[138:139], v[84:85], v[60:61] op_sel_hi:[1,0]
	v_pk_mul_f32 v[142:143], v[86:87], v[60:61] op_sel_hi:[1,0]
	s_waitcnt vmcnt(6)
	v_sub_f32_e32 v117, v117, v61
	v_sub_f32_e32 v116, v116, v61
	v_sub_f32_e32 v119, v119, v61
	global_load_dwordx2 v[102:103], v[162:163], off offset:384
	v_sub_f32_e32 v118, v118, v61
	v_pk_mul_f32 v[64:65], v[80:81], v[60:61] op_sel_hi:[1,0]
	v_pk_mul_f32 v[66:67], v[82:83], v[60:61] op_sel_hi:[1,0]
	global_load_dwordx4 v[52:55], v[148:149], off offset:512
	s_waitcnt vmcnt(7)
	v_sub_f32_e32 v109, v121, v61
	v_sub_f32_e32 v108, v120, v61
	v_sub_f32_e32 v111, v123, v61
	v_sub_f32_e32 v110, v122, v61
	v_pk_fma_f32 v[58:59], v[142:143], v[118:119], v[62:63]
	v_pk_fma_f32 v[56:57], v[138:139], v[116:117], v[126:127]
	global_load_dwordx4 v[60:63], v[128:129], off offset:16
	v_pk_fma_f32 v[66:67], v[66:67], v[110:111], v[130:131]
	v_pk_fma_f32 v[64:65], v[64:65], v[108:109], v[134:135]
	global_store_dwordx4 v[168:169], v[56:59], off offset:512
	global_store_dwordx4 v[168:169], v[64:67], off offset:528
	global_load_dwordx2 v[108:109], v[162:163], off offset:1024
	global_load_dwordx4 v[56:59], v[140:141], off offset:512
	v_lshl_add_u64 v[64:65], v[164:165], 0, s[4:5]
	global_load_dwordx4 v[64:67], v[64:65], off offset:16
	v_pk_fma_f32 v[122:123], v[28:29], v[76:77], v[96:97]
	s_waitcnt vmcnt(12)
	v_cndmask_b32_e64 v29, v100, 0, s[28:29]
	v_cndmask_b32_e64 v28, v101, 1.0, s[28:29]
	v_pk_fma_f32 v[114:115], v[34:35], v[94:95], v[90:91]
	v_pk_fma_f32 v[116:117], v[32:33], v[92:93], v[88:89]
	v_pk_fma_f32 v[32:33], v[42:43], v[78:79], v[98:99]
	v_pk_fma_f32 v[42:43], v[38:39], v[78:79], v[98:99]
	v_pk_fma_f32 v[118:119], v[36:37], v[76:77], v[96:97]
	v_pk_fma_f32 v[120:121], v[30:31], v[78:79], v[98:99]
	v_pk_mul_f32 v[34:35], v[84:85], v[28:29] op_sel_hi:[1,0]
	v_pk_mul_f32 v[30:31], v[86:87], v[28:29] op_sel_hi:[1,0]
	s_waitcnt vmcnt(11)
	v_sub_f32_e32 v37, v73, v29
	v_sub_f32_e32 v36, v72, v29
	v_sub_f32_e32 v39, v75, v29
	v_sub_f32_e32 v38, v74, v29
	v_pk_mul_f32 v[72:73], v[80:81], v[28:29] op_sel_hi:[1,0]
	v_pk_mul_f32 v[74:75], v[82:83], v[28:29] op_sel_hi:[1,0]
	s_waitcnt vmcnt(10)
; #define RES_LOADG(slot, g_) do { const int ro_ = ((g_) >> 2) * HALF + ((g_) & 3) * 16; \
;                 _Pragma("unroll") for (int n = 0; n < 2; ++n) xa[slot][n] = *(const f32x4*)(sl + rbase + (size_t)ro_ * 2048 + bj * HALF + 4 * n); \
;                 ms[slot] = *(const f2_t_*)(stp + 2 * (row0 + ro_)); } while (0)
;     __device__ __forceinline__ void operator()(const f32x4 (&acc)[2][2][4][2], const Unit& u, int wr, int wc, int fr, int fq) const {
;     ...
;             for (int gi = 0; gi < 8; ++gi) {
;                 const int ai = gi >> 2, m = gi & 3;
;                 if (gi + 2 < 8) RES_LOADG((gi + 2) % 3, gi + 2);
;                 asm volatile("" ::: "memory");
;                 float* rowp = xl + rbase + (size_t)(ai * HALF + m * 16) * 2048 + bj * HALF;
;                 const float mean = ln ? ms[gi % 3][0] : 0.f, rstd = ln ? ms[gi % 3][1] : 1.f;
; #pragma unroll
;                 for (int n = 0; n < 2; ++n) { const f32x4 t = ag[n] * rstd;
;                     *(f32x4*)(rowp + 4 * n) = (xa[gi % 3][n] - mean) * t + (ab[n] + mv[n] * acc[ai][bj][m][n]); }
;                 asm volatile("" ::: "memory");
;             }
	v_sub_f32_e32 v69, v69, v29
	v_sub_f32_e32 v68, v68, v29
	v_sub_f32_e32 v71, v71, v29
	v_sub_f32_e32 v70, v70, v29
	v_pk_fma_f32 v[30:31], v[30:31], v[38:39], v[50:51]
	v_pk_fma_f32 v[28:29], v[34:35], v[36:37], v[48:49]
	v_pk_fma_f32 v[34:35], v[74:75], v[70:71], v[32:33]
	v_pk_fma_f32 v[32:33], v[72:73], v[68:69], v[40:41]
	global_store_dwordx4 v[166:167], v[28:31], off offset:512
	global_store_dwordx4 v[166:167], v[32:35], off offset:528
	s_mov_b64 s[4:5], 0x120200
	v_lshl_add_u64 v[110:111], v[164:165], 0, s[4:5]
	global_load_dwordx4 v[28:31], v[132:133], off offset:512
	global_load_dwordx4 v[32:35], v[110:111], off offset:16
	global_load_dwordx2 v[68:69], v[162:163], off offset:1152
	s_mov_b64 s[4:5], 0x140200
	v_lshl_add_u64 v[112:113], v[164:165], 0, s[4:5]
	s_mov_b64 s[4:5], 0x160200
	s_waitcnt vmcnt(12)
	v_cndmask_b32_e64 v37, v102, 0, s[28:29]
	v_cndmask_b32_e64 v36, v103, 1.0, s[28:29]
	v_pk_mul_f32 v[40:41], v[84:85], v[36:37] op_sel_hi:[1,0]
	v_pk_mul_f32 v[38:39], v[86:87], v[36:37] op_sel_hi:[1,0]
	s_waitcnt vmcnt(11)
	v_sub_f32_e32 v49, v53, v37
	v_sub_f32_e32 v48, v52, v37
	v_sub_f32_e32 v51, v55, v37
	v_sub_f32_e32 v50, v54, v37
	v_pk_mul_f32 v[52:53], v[80:81], v[36:37] op_sel_hi:[1,0]
	v_pk_mul_f32 v[54:55], v[82:83], v[36:37] op_sel_hi:[1,0]
	v_pk_fma_f32 v[38:39], v[38:39], v[50:51], v[46:47]
	s_waitcnt vmcnt(10)
	v_sub_f32_e32 v61, v61, v37
	v_sub_f32_e32 v60, v60, v37
	v_sub_f32_e32 v63, v63, v37
	v_sub_f32_e32 v62, v62, v37
	v_pk_fma_f32 v[36:37], v[40:41], v[48:49], v[44:45]
	v_pk_fma_f32 v[42:43], v[54:55], v[62:63], v[42:43]
	v_pk_fma_f32 v[40:41], v[52:53], v[60:61], v[118:119]
	s_waitcnt vmcnt(7)
	v_cndmask_b32_e64 v45, v108, 0, s[28:29]
	v_cndmask_b32_e64 v44, v109, 1.0, s[28:29]
	global_store_dwordx4 v[148:149], v[36:39], off offset:512
	global_store_dwordx4 v[148:149], v[40:43], off offset:528
	s_waitcnt vmcnt(8)
	v_sub_f32_e32 v49, v57, v45
	v_sub_f32_e32 v48, v56, v45
	v_pk_mul_f32 v[40:41], v[84:85], v[44:45] op_sel_hi:[1,0]
	v_pk_mul_f32 v[42:43], v[86:87], v[44:45] op_sel_hi:[1,0]
	v_sub_f32_e32 v47, v59, v45
	v_sub_f32_e32 v46, v58, v45
	global_load_dwordx2 v[52:53], v[162:163], off offset:1280
	v_pk_mul_f32 v[54:55], v[80:81], v[44:45] op_sel_hi:[1,0]
	v_pk_mul_f32 v[50:51], v[82:83], v[44:45] op_sel_hi:[1,0]
	s_waitcnt vmcnt(8)
	v_sub_f32_e32 v57, v65, v45
	v_sub_f32_e32 v56, v64, v45
	v_sub_f32_e32 v59, v67, v45
	v_sub_f32_e32 v58, v66, v45
	v_pk_fma_f32 v[42:43], v[42:43], v[46:47], v[114:115]
	v_pk_fma_f32 v[40:41], v[40:41], v[48:49], v[116:117]
	global_load_dwordx4 v[36:39], v[104:105], off offset:512
	global_load_dwordx4 v[44:47], v[112:113], off offset:16
	v_pk_fma_f32 v[50:51], v[50:51], v[58:59], v[120:121]
	v_pk_fma_f32 v[48:49], v[54:55], v[56:57], v[122:123]
	global_store_dwordx4 v[140:141], v[40:43], off offset:512
	global_store_dwordx4 v[140:141], v[48:51], off offset:528
	global_load_dwordx2 v[54:55], v[162:163], off offset:1408
	global_load_dwordx4 v[40:43], v[106:107], off offset:512
	v_lshl_add_u64 v[48:49], v[164:165], 0, s[4:5]
	global_load_dwordx4 v[48:51], v[48:49], off offset:16
	v_pk_fma_f32 v[62:63], v[4:5], v[76:77], v[96:97]
	v_pk_fma_f32 v[56:57], v[10:11], v[78:79], v[98:99]
	v_pk_fma_f32 v[58:59], v[8:9], v[76:77], v[96:97]
	s_waitcnt vmcnt(10)
	v_cndmask_b32_e64 v5, v68, 0, s[28:29]
	v_cndmask_b32_e64 v4, v69, 1.0, s[28:29]
	v_pk_fma_f32 v[60:61], v[6:7], v[78:79], v[98:99]
	v_pk_mul_f32 v[8:9], v[84:85], v[4:5] op_sel_hi:[1,0]
	v_pk_mul_f32 v[6:7], v[86:87], v[4:5] op_sel_hi:[1,0]
	v_sub_f32_e32 v11, v29, v5
	v_sub_f32_e32 v10, v28, v5
	v_sub_f32_e32 v29, v31, v5
	v_sub_f32_e32 v28, v30, v5
	v_pk_mul_f32 v[30:31], v[80:81], v[4:5] op_sel_hi:[1,0]
	v_pk_mul_f32 v[64:65], v[82:83], v[4:5] op_sel_hi:[1,0]
	v_sub_f32_e32 v33, v33, v5
	v_sub_f32_e32 v32, v32, v5
	v_sub_f32_e32 v35, v35, v5
	v_sub_f32_e32 v34, v34, v5
	v_pk_fma_f32 v[6:7], v[6:7], v[28:29], v[26:27]
	v_pk_fma_f32 v[4:5], v[8:9], v[10:11], v[24:25]
	v_pk_fma_f32 v[10:11], v[64:65], v[34:35], v[14:15]
	v_pk_fma_f32 v[8:9], v[30:31], v[32:33], v[12:13]
	global_store_dwordx4 v[132:133], v[4:7], off offset:512
	global_store_dwordx4 v[132:133], v[8:11], off offset:528
	s_waitcnt vmcnt(9)
	v_cndmask_b32_e64 v5, v52, 0, s[28:29]
	v_cndmask_b32_e64 v4, v53, 1.0, s[28:29]
	v_pk_mul_f32 v[8:9], v[84:85], v[4:5] op_sel_hi:[1,0]
	v_pk_mul_f32 v[6:7], v[86:87], v[4:5] op_sel_hi:[1,0]
	v_pk_mul_f32 v[14:15], v[80:81], v[4:5] op_sel_hi:[1,0]
	v_pk_mul_f32 v[24:25], v[82:83], v[4:5] op_sel_hi:[1,0]
	s_waitcnt vmcnt(8)
	v_sub_f32_e32 v11, v37, v5
	v_sub_f32_e32 v10, v36, v5
	v_sub_f32_e32 v13, v39, v5
	v_sub_f32_e32 v12, v38, v5
	s_waitcnt vmcnt(7)
	v_sub_f32_e32 v27, v45, v5
	v_sub_f32_e32 v26, v44, v5
	v_sub_f32_e32 v29, v47, v5
	v_sub_f32_e32 v28, v46, v5
	v_pk_fma_f32 v[6:7], v[6:7], v[12:13], v[22:23]
	v_pk_fma_f32 v[4:5], v[8:9], v[10:11], v[20:21]
	v_pk_fma_f32 v[10:11], v[24:25], v[28:29], v[56:57]
	v_pk_fma_f32 v[8:9], v[14:15], v[26:27], v[58:59]
	s_waitcnt vmcnt(4)
	v_cndmask_b32_e64 v22, v54, 0, s[28:29]
	v_cndmask_b32_e64 v12, v55, 1.0, s[28:29]
	global_store_dwordx4 v[104:105], v[4:7], off offset:512
	global_store_dwordx4 v[104:105], v[8:11], off offset:528
	v_pk_mul_f32 v[14:15], v[80:81], v[12:13] op_sel_hi:[1,0]
	v_pk_mul_f32 v[4:5], v[84:85], v[12:13] op_sel_hi:[1,0]
	v_pk_mul_f32 v[6:7], v[86:87], v[12:13] op_sel_hi:[1,0]
	s_waitcnt vmcnt(5)
	v_sub_f32_e32 v9, v41, v22
	v_sub_f32_e32 v8, v40, v22
	v_sub_f32_e32 v11, v43, v22
	v_sub_f32_e32 v10, v42, v22
	v_pk_mul_f32 v[12:13], v[82:83], v[12:13] op_sel_hi:[1,0]
	s_waitcnt vmcnt(4)
	v_sub_f32_e32 v21, v49, v22
	v_sub_f32_e32 v20, v48, v22
	v_sub_f32_e32 v23, v51, v22
	v_sub_f32_e32 v22, v50, v22
	v_pk_fma_f32 v[6:7], v[6:7], v[10:11], v[18:19]
	v_pk_fma_f32 v[4:5], v[4:5], v[8:9], v[16:17]
	v_pk_fma_f32 v[10:11], v[12:13], v[22:23], v[60:61]
	v_pk_fma_f32 v[8:9], v[14:15], v[20:21], v[62:63]
	global_store_dwordx4 v[106:107], v[4:7], off offset:512
	global_store_dwordx4 v[106:107], v[8:11], off offset:528
	s_cbranch_vccnz .LBB0_1318
	s_andn2_b64 vcc, exec, s[18:19]
	s_cbranch_vccnz .LBB0_1317
	s_barrier
	s_branch .LBB0_1317
